# v95 + mout readout: per-quad vmcnt waits that only waited for the previous store removed (operands already resident)
# baseline (speedup 1.0000x reference)
.LBB1_99:
	v_mul_f32_e32 v116, v33, v35
	v_cvt_pk_bf16_f32 v32, v32, v36
	v_cvt_pk_bf16_f32 v33, v41, v38
	ds_write_b64 v43, v[32:33] offset:4576
	v_add_u32_e32 v56, v158, v42
	v_mul_f32_e32 v110, v45, v47
	v_mul_f32_e32 v114, v44, v46
	v_mul_f32_e32 v112, v34, v37
	s_waitcnt lgkmcnt(0)
	s_barrier
	ds_read_b128 v[32:35], v56
	ds_read_b128 v[36:39], v56 offset:64
	ds_read_b128 v[40:43], v56 offset:128
	ds_read_b128 v[88:91], v56 offset:192
	ds_read_b128 v[44:47], v56 offset:4352
	ds_read_b128 v[48:51], v56 offset:4416
	ds_read_b128 v[52:55], v56 offset:4480
	ds_read_b128 v[92:95], v56 offset:4544
	ds_read_b128 v[56:59], v157 offset:34816
	ds_read_b128 v[60:63], v157 offset:39168
	ds_read_b128 v[64:67], v157 offset:43520
	ds_read_b128 v[68:71], v157 offset:47872
	ds_read_b128 v[72:75], v157 offset:52224
	ds_read_b128 v[76:79], v157 offset:56576
	ds_read_b128 v[80:83], v157 offset:60928
	ds_read_b128 v[84:87], v157 offset:65280
	s_setprio 1
	s_waitcnt lgkmcnt(7)
	v_mfma_f32_16x16x32_bf16 v[96:99], v[56:59], v[32:35], 0
	v_mfma_f32_16x16x32_bf16 v[56:59], v[56:59], v[44:47], 0
	s_waitcnt lgkmcnt(6)
	v_mfma_f32_16x16x32_bf16 v[100:103], v[60:63], v[32:35], 0
	v_mfma_f32_16x16x32_bf16 v[60:63], v[60:63], v[44:47], 0
	s_waitcnt lgkmcnt(5)
	v_mfma_f32_16x16x32_bf16 v[118:121], v[64:67], v[32:35], 0
	v_mfma_f32_16x16x32_bf16 v[64:67], v[64:67], v[44:47], 0
	s_waitcnt lgkmcnt(4)
	v_mfma_f32_16x16x32_bf16 v[122:125], v[68:71], v[32:35], 0
	v_mfma_f32_16x16x32_bf16 v[68:71], v[68:71], v[44:47], 0
	s_waitcnt lgkmcnt(3)
	v_mfma_f32_16x16x32_bf16 v[130:133], v[72:75], v[32:35], 0
	v_mfma_f32_16x16x32_bf16 v[72:75], v[72:75], v[44:47], 0
	s_waitcnt lgkmcnt(2)
	v_mfma_f32_16x16x32_bf16 v[134:137], v[76:79], v[32:35], 0
	v_mfma_f32_16x16x32_bf16 v[76:79], v[76:79], v[44:47], 0
	s_waitcnt lgkmcnt(1)
	v_mfma_f32_16x16x32_bf16 v[138:141], v[80:83], v[32:35], 0
	v_mfma_f32_16x16x32_bf16 v[80:83], v[80:83], v[44:47], 0
	s_waitcnt lgkmcnt(0)
	v_mfma_f32_16x16x32_bf16 v[32:35], v[84:87], v[32:35], 0
	v_mfma_f32_16x16x32_bf16 v[44:47], v[84:87], v[44:47], 0
	s_setprio 0
	ds_read_b128 v[84:87], v157 offset:34880
	ds_read_b128 v[142:145], v157 offset:39232
	ds_read_b128 v[146:149], v157 offset:43584
	ds_read_b128 v[150:153], v157 offset:47936
	ds_read_b128 v[158:161], v157 offset:52288
	ds_read_b128 v[188:191], v157 offset:56640
	ds_read_b128 v[192:195], v157 offset:60992
	ds_read_b128 v[196:199], v157 offset:65344
	s_setprio 1
	s_waitcnt lgkmcnt(7)
	v_mfma_f32_16x16x32_bf16 v[96:99], v[84:87], v[36:39], v[96:99]
	v_mfma_f32_16x16x32_bf16 v[56:59], v[84:87], v[48:51], v[56:59]
	s_waitcnt lgkmcnt(6)
	v_mfma_f32_16x16x32_bf16 v[84:87], v[142:145], v[36:39], v[100:103]
	v_mfma_f32_16x16x32_bf16 v[60:63], v[142:145], v[48:51], v[60:63]
	s_waitcnt lgkmcnt(5)
	v_mfma_f32_16x16x32_bf16 v[100:103], v[146:149], v[36:39], v[118:121]
	v_mfma_f32_16x16x32_bf16 v[64:67], v[146:149], v[48:51], v[64:67]
	s_waitcnt lgkmcnt(4)
	v_mfma_f32_16x16x32_bf16 v[118:121], v[150:153], v[36:39], v[122:125]
	v_mfma_f32_16x16x32_bf16 v[68:71], v[150:153], v[48:51], v[68:71]
	s_waitcnt lgkmcnt(3)
	v_mfma_f32_16x16x32_bf16 v[122:125], v[158:161], v[36:39], v[130:133]
	v_mfma_f32_16x16x32_bf16 v[72:75], v[158:161], v[48:51], v[72:75]
	s_waitcnt lgkmcnt(2)
	v_mfma_f32_16x16x32_bf16 v[130:133], v[188:191], v[36:39], v[134:137]
	v_mfma_f32_16x16x32_bf16 v[76:79], v[188:191], v[48:51], v[76:79]
	s_waitcnt lgkmcnt(1)
	v_mfma_f32_16x16x32_bf16 v[134:137], v[192:195], v[36:39], v[138:141]
	v_mfma_f32_16x16x32_bf16 v[80:83], v[192:195], v[48:51], v[80:83]
	s_waitcnt lgkmcnt(0)
	v_mfma_f32_16x16x32_bf16 v[32:35], v[196:199], v[36:39], v[32:35]
	v_mfma_f32_16x16x32_bf16 v[36:39], v[196:199], v[48:51], v[44:47]
	s_setprio 0
	s_nop 1
	ds_read_b128 v[44:47], v157 offset:34944
	ds_read_b128 v[48:51], v157 offset:39296
	ds_read_b128 v[138:141], v157 offset:43648
	ds_read_b128 v[142:145], v157 offset:48000
	ds_read_b128 v[146:149], v157 offset:52352
	ds_read_b128 v[150:153], v157 offset:56704
	ds_read_b128 v[158:161], v157 offset:61056
	ds_read_b128 v[188:191], v157 offset:65408
	s_setprio 1
	s_waitcnt lgkmcnt(7)
	v_mfma_f32_16x16x32_bf16 v[96:99], v[44:47], v[40:43], v[96:99]
	v_mfma_f32_16x16x32_bf16 v[44:47], v[44:47], v[52:55], v[56:59]
	s_waitcnt lgkmcnt(6)
	v_mfma_f32_16x16x32_bf16 v[56:59], v[48:51], v[40:43], v[84:87]
	v_mfma_f32_16x16x32_bf16 v[48:51], v[48:51], v[52:55], v[60:63]
	s_waitcnt lgkmcnt(5)
	v_mfma_f32_16x16x32_bf16 v[60:63], v[138:141], v[40:43], v[100:103]
	v_mfma_f32_16x16x32_bf16 v[64:67], v[138:141], v[52:55], v[64:67]
	s_waitcnt lgkmcnt(4)
	v_mfma_f32_16x16x32_bf16 v[84:87], v[142:145], v[40:43], v[118:121]
	v_mfma_f32_16x16x32_bf16 v[68:71], v[142:145], v[52:55], v[68:71]
	s_waitcnt lgkmcnt(3)
	v_mfma_f32_16x16x32_bf16 v[100:103], v[146:149], v[40:43], v[122:125]
	v_mfma_f32_16x16x32_bf16 v[72:75], v[146:149], v[52:55], v[72:75]
	s_waitcnt lgkmcnt(2)
	v_mfma_f32_16x16x32_bf16 v[118:121], v[150:153], v[40:43], v[130:133]
	v_mfma_f32_16x16x32_bf16 v[76:79], v[150:153], v[52:55], v[76:79]
	s_waitcnt lgkmcnt(1)
	v_mfma_f32_16x16x32_bf16 v[122:125], v[158:161], v[40:43], v[134:137]
	v_mfma_f32_16x16x32_bf16 v[130:133], v[158:161], v[52:55], v[80:83]
	s_waitcnt lgkmcnt(0)
	v_mfma_f32_16x16x32_bf16 v[134:137], v[188:191], v[40:43], v[32:35]
	v_mfma_f32_16x16x32_bf16 v[138:141], v[188:191], v[52:55], v[36:39]
	s_setprio 0
	s_nop 1
	ds_read_b128 v[36:39], v157 offset:35008
	ds_read_b128 v[52:55], v157 offset:39360
	ds_read_b128 v[80:83], v157 offset:43712
	ds_read_b128 v[142:145], v157 offset:48064
	ds_read_b128 v[146:149], v157 offset:52416
	ds_read_b128 v[150:153], v157 offset:56768
	ds_read_b128 v[158:161], v157 offset:61120
	ds_read_b128 v[188:191], v157 offset:65472
	s_setprio 1
	s_waitcnt lgkmcnt(7)
	v_mfma_f32_16x16x32_bf16 v[32:35], v[36:39], v[88:91], v[96:99]
	v_mfma_f32_16x16x32_bf16 v[36:39], v[36:39], v[92:95], v[44:47]
	s_waitcnt lgkmcnt(6)
	v_mfma_f32_16x16x32_bf16 v[40:43], v[52:55], v[88:91], v[56:59]
	v_mfma_f32_16x16x32_bf16 v[44:47], v[52:55], v[92:95], v[48:51]
	s_waitcnt lgkmcnt(5)
	v_mfma_f32_16x16x32_bf16 v[48:51], v[80:83], v[88:91], v[60:63]
	v_mfma_f32_16x16x32_bf16 v[52:55], v[80:83], v[92:95], v[64:67]
	s_waitcnt lgkmcnt(4)
	v_mfma_f32_16x16x32_bf16 v[56:59], v[142:145], v[88:91], v[84:87]
	v_mfma_f32_16x16x32_bf16 v[60:63], v[142:145], v[92:95], v[68:71]
	s_waitcnt lgkmcnt(3)
	v_mfma_f32_16x16x32_bf16 v[64:67], v[146:149], v[88:91], v[100:103]
	v_mfma_f32_16x16x32_bf16 v[68:71], v[146:149], v[92:95], v[72:75]
	s_waitcnt lgkmcnt(2)
	v_mfma_f32_16x16x32_bf16 v[72:75], v[150:153], v[88:91], v[118:121]
	v_mfma_f32_16x16x32_bf16 v[76:79], v[150:153], v[92:95], v[76:79]
	s_waitcnt lgkmcnt(1)
	v_mfma_f32_16x16x32_bf16 v[80:83], v[158:161], v[88:91], v[122:125]
	v_mfma_f32_16x16x32_bf16 v[84:87], v[158:161], v[92:95], v[130:133]
	s_waitcnt lgkmcnt(0)
	v_mfma_f32_16x16x32_bf16 v[88:91], v[188:191], v[88:91], v[134:137]
	v_mfma_f32_16x16x32_bf16 v[92:95], v[188:191], v[92:95], v[138:141]
	s_setprio 0
	s_lshl_b64 s[4:5], s[70:71], 15
	s_add_u32 s4, s80, s4
	s_addc_u32 s5, s81, s5
	v_lshlrev_b64 v[96:97], 8, v[104:105]
	v_lshl_add_u64 v[98:99], s[4:5], 0, v[96:97]
	s_lshl_b64 s[4:5], s[68:69], 15
	s_add_u32 s4, s80, s4
	s_addc_u32 s5, s81, s5
	v_lshl_add_u64 v[100:101], v[98:99], 0, v[128:129]
	v_lshl_add_u64 v[96:97], s[4:5], 0, v[96:97]
	s_barrier
	v_lshl_add_u64 v[102:103], v[96:97], 0, v[128:129]
	global_load_dwordx4 v[204:207], v[100:101], off
	s_movk_i32 s5, 0x2000
	v_add_co_u32_e32 v104, vcc, s5, v100
	s_movk_i32 s2, 0x4000
	s_nop 0
	v_addc_co_u32_e32 v105, vcc, 0, v101, vcc
	s_movk_i32 s4, 0x6000
	s_movk_i32 s6, 0x7000
	v_mov_b64_e32 v[132:133], v[10:11]
	v_mov_b64_e32 v[130:131], v[8:9]
	v_mov_b64_e32 v[136:137], v[6:7]
	v_mov_b64_e32 v[134:135], v[4:5]
	v_mov_b64_e32 v[140:141], v[2:3]
	v_mov_b64_e32 v[138:139], v[0:1]
	global_load_dwordx4 v[208:211], v[104:105], off offset:-4096
	global_load_dwordx4 v[216:219], v[104:105], off
	v_add_co_u32_e32 v104, vcc, s2, v100
	v_addc_co_u32_e32 v105, vcc, 0, v101, vcc
	global_load_dwordx4 v[220:223], v[104:105], off offset:-4096
	global_load_dwordx4 v[224:227], v[104:105], off
	v_add_co_u32_e32 v104, vcc, s4, v100
	v_addc_co_u32_e32 v105, vcc, 0, v101, vcc
	global_load_dwordx4 v[228:231], v[104:105], off offset:-4096
	global_load_dwordx4 v[232:235], v[104:105], off
	v_add_co_u32_e32 v96, vcc, s6, v100
	s_nop 1
	v_addc_co_u32_e32 v97, vcc, 0, v101, vcc
	global_load_dwordx4 v[236:239], v[96:97], off
	s_waitcnt vmcnt(0)
	ds_write_b128 v107, v[204:207]
	ds_write_b128 v107, v[208:211] offset:4352
	ds_write_b128 v107, v[216:219] offset:8704
	ds_write_b128 v107, v[220:223] offset:13056
	ds_write_b128 v107, v[224:227] offset:17408
	ds_write_b128 v107, v[228:231] offset:21760
	ds_write_b128 v107, v[232:235] offset:26112
	ds_write_b128 v107, v[236:239] offset:30464
	v_add_co_u32_e32 v100, vcc, s5, v102
	global_load_dwordx4 v[204:207], v[102:103], off
	v_addc_co_u32_e32 v101, vcc, 0, v103, vcc
	global_load_dwordx4 v[208:211], v[100:101], off offset:-4096
	global_load_dwordx4 v[216:219], v[100:101], off
	v_add_co_u32_e32 v100, vcc, s2, v102
	v_addc_co_u32_e32 v101, vcc, 0, v103, vcc
	global_load_dwordx4 v[220:223], v[100:101], off offset:-4096
	global_load_dwordx4 v[224:227], v[100:101], off
	v_add_co_u32_e32 v100, vcc, s4, v102
	v_addc_co_u32_e32 v101, vcc, 0, v103, vcc
	global_load_dwordx4 v[228:231], v[100:101], off offset:-4096
	global_load_dwordx4 v[232:235], v[100:101], off
	v_add_co_u32_e32 v96, vcc, s6, v102
	s_nop 1
	v_addc_co_u32_e32 v97, vcc, 0, v103, vcc
	global_load_dwordx4 v[236:239], v[96:97], off
	s_waitcnt vmcnt(0)
	ds_write_b128 v107, v[204:207] offset:34816
	ds_write_b128 v107, v[208:211] offset:39168
	ds_write_b128 v107, v[216:219] offset:43520
	ds_write_b128 v107, v[220:223] offset:47872
	ds_write_b128 v107, v[224:227] offset:52224
	ds_write_b128 v107, v[228:231] offset:56576
	ds_write_b128 v107, v[232:235] offset:60928
	ds_write_b128 v107, v[236:239] offset:65280
	v_mov_b64_e32 v[98:99], v[30:31]
	v_mov_b64_e32 v[96:97], v[28:29]
	s_waitcnt lgkmcnt(0)
	s_barrier
	s_nop 0
	v_lshlrev_b32_e32 v100, 16, v96
	v_and_b32_e32 v101, 0xffff0000, v96
	v_pk_mul_f32 v[100:101], v[116:117], v[100:101] op_sel_hi:[0,1]
	v_cvt_pk_bf16_f32 v96, v100, v101
	v_lshlrev_b32_e32 v100, 16, v97
	v_and_b32_e32 v101, 0xffff0000, v97
	v_pk_mul_f32 v[100:101], v[116:117], v[100:101] op_sel_hi:[0,1]
	v_cvt_pk_bf16_f32 v97, v100, v101
	v_lshlrev_b32_e32 v100, 16, v98
	v_and_b32_e32 v101, 0xffff0000, v98
	v_pk_mul_f32 v[100:101], v[116:117], v[100:101] op_sel_hi:[0,1]
	v_cvt_pk_bf16_f32 v98, v100, v101
	v_lshlrev_b32_e32 v100, 16, v99
	v_and_b32_e32 v101, 0xffff0000, v99
	v_pk_mul_f32 v[100:101], v[116:117], v[100:101] op_sel_hi:[0,1]
	v_cvt_pk_bf16_f32 v99, v100, v101
	v_mov_b64_e32 v[102:103], v[26:27]
	v_mov_b64_e32 v[100:101], v[24:25]
	s_nop 0
	v_lshlrev_b32_e32 v104, 16, v100
	v_and_b32_e32 v105, 0xffff0000, v100
	v_pk_mul_f32 v[104:105], v[114:115], v[104:105] op_sel_hi:[0,1]
	v_cvt_pk_bf16_f32 v100, v104, v105
	v_lshlrev_b32_e32 v104, 16, v101
	v_and_b32_e32 v105, 0xffff0000, v101
	v_pk_mul_f32 v[104:105], v[114:115], v[104:105] op_sel_hi:[0,1]
	v_cvt_pk_bf16_f32 v101, v104, v105
	v_lshlrev_b32_e32 v104, 16, v102
	v_and_b32_e32 v105, 0xffff0000, v102
	v_pk_mul_f32 v[104:105], v[114:115], v[104:105] op_sel_hi:[0,1]
	v_cvt_pk_bf16_f32 v102, v104, v105
	v_lshlrev_b32_e32 v104, 16, v103
	v_and_b32_e32 v105, 0xffff0000, v103
	v_pk_mul_f32 v[104:105], v[114:115], v[104:105] op_sel_hi:[0,1]
	v_cvt_pk_bf16_f32 v103, v104, v105
	v_mov_b64_e32 v[106:107], v[22:23]
	v_mov_b64_e32 v[104:105], v[20:21]
	s_nop 0
	v_lshlrev_b32_e32 v118, 16, v104
	v_and_b32_e32 v119, 0xffff0000, v104
	v_pk_mul_f32 v[118:119], v[116:117], v[118:119] op_sel_hi:[0,1]
	v_cvt_pk_bf16_f32 v104, v118, v119
	v_lshlrev_b32_e32 v118, 16, v105
	v_and_b32_e32 v119, 0xffff0000, v105
	v_pk_mul_f32 v[118:119], v[116:117], v[118:119] op_sel_hi:[0,1]
	v_cvt_pk_bf16_f32 v105, v118, v119
	v_lshlrev_b32_e32 v118, 16, v106
	v_and_b32_e32 v119, 0xffff0000, v106
	v_pk_mul_f32 v[118:119], v[116:117], v[118:119] op_sel_hi:[0,1]
	v_cvt_pk_bf16_f32 v106, v118, v119
	v_lshlrev_b32_e32 v118, 16, v107
	v_and_b32_e32 v119, 0xffff0000, v107
	v_pk_mul_f32 v[118:119], v[116:117], v[118:119] op_sel_hi:[0,1]
	v_cvt_pk_bf16_f32 v107, v118, v119
	v_mov_b64_e32 v[120:121], v[18:19]
	v_mov_b64_e32 v[118:119], v[16:17]
	s_nop 0
	v_lshlrev_b32_e32 v122, 16, v118
	v_and_b32_e32 v123, 0xffff0000, v118
	v_pk_mul_f32 v[122:123], v[114:115], v[122:123] op_sel_hi:[0,1]
	v_cvt_pk_bf16_f32 v118, v122, v123
	v_lshlrev_b32_e32 v122, 16, v119
	v_and_b32_e32 v123, 0xffff0000, v119
	v_pk_mul_f32 v[122:123], v[114:115], v[122:123] op_sel_hi:[0,1]
	v_cvt_pk_bf16_f32 v119, v122, v123
	v_lshlrev_b32_e32 v122, 16, v120
	v_and_b32_e32 v123, 0xffff0000, v120
	v_pk_mul_f32 v[122:123], v[114:115], v[122:123] op_sel_hi:[0,1]
	v_cvt_pk_bf16_f32 v120, v122, v123
	v_lshlrev_b32_e32 v122, 16, v121
	v_and_b32_e32 v123, 0xffff0000, v121
	v_pk_mul_f32 v[122:123], v[114:115], v[122:123] op_sel_hi:[0,1]
	v_cvt_pk_bf16_f32 v121, v122, v123
	v_mov_b64_e32 v[124:125], v[14:15]
	v_mov_b64_e32 v[122:123], v[12:13]
	s_nop 0
	v_lshlrev_b32_e32 v126, 16, v122
	v_and_b32_e32 v127, 0xffff0000, v122
	v_pk_mul_f32 v[126:127], v[116:117], v[126:127] op_sel_hi:[0,1]
	v_cvt_pk_bf16_f32 v122, v126, v127
	v_lshlrev_b32_e32 v126, 16, v123
	v_and_b32_e32 v127, 0xffff0000, v123
	v_pk_mul_f32 v[126:127], v[116:117], v[126:127] op_sel_hi:[0,1]
	v_cvt_pk_bf16_f32 v123, v126, v127
	v_lshlrev_b32_e32 v126, 16, v124
	v_and_b32_e32 v127, 0xffff0000, v124
	v_pk_mul_f32 v[126:127], v[116:117], v[126:127] op_sel_hi:[0,1]
	v_cvt_pk_bf16_f32 v124, v126, v127
	v_lshlrev_b32_e32 v126, 16, v125
	v_and_b32_e32 v127, 0xffff0000, v125
	v_pk_mul_f32 v[126:127], v[116:117], v[126:127] op_sel_hi:[0,1]
	v_cvt_pk_bf16_f32 v125, v126, v127
	v_lshlrev_b32_e32 v126, 16, v130
	v_and_b32_e32 v127, 0xffff0000, v130
	v_pk_mul_f32 v[126:127], v[114:115], v[126:127] op_sel_hi:[0,1]
	v_cvt_pk_bf16_f32 v130, v126, v127
	v_lshlrev_b32_e32 v126, 16, v131
	v_and_b32_e32 v127, 0xffff0000, v131
	v_pk_mul_f32 v[126:127], v[114:115], v[126:127] op_sel_hi:[0,1]
	v_cvt_pk_bf16_f32 v131, v126, v127
	v_lshlrev_b32_e32 v126, 16, v132
	v_and_b32_e32 v127, 0xffff0000, v132
	v_pk_mul_f32 v[126:127], v[114:115], v[126:127] op_sel_hi:[0,1]
	v_cvt_pk_bf16_f32 v132, v126, v127
	v_lshlrev_b32_e32 v126, 16, v133
	v_and_b32_e32 v127, 0xffff0000, v133
	v_pk_mul_f32 v[126:127], v[114:115], v[126:127] op_sel_hi:[0,1]
	v_cvt_pk_bf16_f32 v133, v126, v127
	v_lshlrev_b32_e32 v126, 16, v134
	v_and_b32_e32 v127, 0xffff0000, v134
	v_pk_mul_f32 v[126:127], v[116:117], v[126:127] op_sel_hi:[0,1]
	v_cvt_pk_bf16_f32 v134, v126, v127
	v_lshlrev_b32_e32 v126, 16, v135
	v_and_b32_e32 v127, 0xffff0000, v135
	v_pk_mul_f32 v[126:127], v[116:117], v[126:127] op_sel_hi:[0,1]
	v_cvt_pk_bf16_f32 v135, v126, v127
	v_lshlrev_b32_e32 v126, 16, v136
	v_and_b32_e32 v127, 0xffff0000, v136
	v_pk_mul_f32 v[126:127], v[116:117], v[126:127] op_sel_hi:[0,1]
	v_cvt_pk_bf16_f32 v136, v126, v127
	v_lshlrev_b32_e32 v126, 16, v137
	v_and_b32_e32 v127, 0xffff0000, v137
	v_pk_mul_f32 v[116:117], v[116:117], v[126:127] op_sel_hi:[0,1]
	v_cvt_pk_bf16_f32 v137, v116, v117
	v_lshlrev_b32_e32 v116, 16, v138
	v_and_b32_e32 v117, 0xffff0000, v138
	v_pk_mul_f32 v[116:117], v[114:115], v[116:117] op_sel_hi:[0,1]
	v_cvt_pk_bf16_f32 v138, v116, v117
	v_lshlrev_b32_e32 v116, 16, v139
	v_and_b32_e32 v117, 0xffff0000, v139
	v_pk_mul_f32 v[116:117], v[114:115], v[116:117] op_sel_hi:[0,1]
	v_cvt_pk_bf16_f32 v139, v116, v117
	v_lshlrev_b32_e32 v116, 16, v140
	v_and_b32_e32 v117, 0xffff0000, v140
	v_pk_mul_f32 v[116:117], v[114:115], v[116:117] op_sel_hi:[0,1]
	v_cvt_pk_bf16_f32 v140, v116, v117
	v_lshlrev_b32_e32 v116, 16, v141
	v_and_b32_e32 v117, 0xffff0000, v141
	v_pk_mul_f32 v[114:115], v[114:115], v[116:117] op_sel_hi:[0,1]
	v_cvt_pk_bf16_f32 v141, v114, v115
	ds_read_b128 v[114:117], v157
	ds_read_b128 v[142:145], v157 offset:4352
	ds_read_b128 v[146:149], v157 offset:8704
	ds_read_b128 v[150:153], v157 offset:13056
	ds_read_b128 v[158:161], v157 offset:17408
	ds_read_b128 v[188:191], v157 offset:21760
	ds_read_b128 v[192:195], v157 offset:26112
	ds_read_b128 v[196:199], v157 offset:30464
	s_setprio 1
	s_waitcnt lgkmcnt(7)
	v_mfma_f32_16x16x32_bf16 v[32:35], v[114:117], v[96:99], v[32:35]
	v_mfma_f32_16x16x32_bf16 v[36:39], v[114:117], v[100:103], v[36:39]
	s_waitcnt lgkmcnt(6)
	v_mfma_f32_16x16x32_bf16 v[40:43], v[142:145], v[96:99], v[40:43]
	v_mfma_f32_16x16x32_bf16 v[44:47], v[142:145], v[100:103], v[44:47]
	s_waitcnt lgkmcnt(5)
	v_mfma_f32_16x16x32_bf16 v[48:51], v[146:149], v[96:99], v[48:51]
	v_mfma_f32_16x16x32_bf16 v[52:55], v[146:149], v[100:103], v[52:55]
	s_waitcnt lgkmcnt(4)
	v_mfma_f32_16x16x32_bf16 v[56:59], v[150:153], v[96:99], v[56:59]
	v_mfma_f32_16x16x32_bf16 v[60:63], v[150:153], v[100:103], v[60:63]
	s_waitcnt lgkmcnt(3)
	v_mfma_f32_16x16x32_bf16 v[64:67], v[158:161], v[96:99], v[64:67]
	v_mfma_f32_16x16x32_bf16 v[68:71], v[158:161], v[100:103], v[68:71]
	s_waitcnt lgkmcnt(2)
	v_mfma_f32_16x16x32_bf16 v[72:75], v[188:191], v[96:99], v[72:75]
	v_mfma_f32_16x16x32_bf16 v[76:79], v[188:191], v[100:103], v[76:79]
	s_waitcnt lgkmcnt(1)
	v_mfma_f32_16x16x32_bf16 v[80:83], v[192:195], v[96:99], v[80:83]
	v_mfma_f32_16x16x32_bf16 v[84:87], v[192:195], v[100:103], v[84:87]
	s_waitcnt lgkmcnt(0)
	v_mfma_f32_16x16x32_bf16 v[88:91], v[196:199], v[96:99], v[88:91]
	v_mfma_f32_16x16x32_bf16 v[92:95], v[196:199], v[100:103], v[92:95]
	s_setprio 0
	ds_read_b128 v[96:99], v157 offset:64
	ds_read_b128 v[100:103], v157 offset:4416
	ds_read_b128 v[114:117], v157 offset:8768
	ds_read_b128 v[142:145], v157 offset:13120
	ds_read_b128 v[146:149], v157 offset:17472
	ds_read_b128 v[150:153], v157 offset:21824
	ds_read_b128 v[158:161], v157 offset:26176
	ds_read_b128 v[188:191], v157 offset:30528
	s_setprio 1
	s_waitcnt lgkmcnt(7)
	v_mfma_f32_16x16x32_bf16 v[32:35], v[96:99], v[104:107], v[32:35]
	v_mfma_f32_16x16x32_bf16 v[36:39], v[96:99], v[118:121], v[36:39]
	s_waitcnt lgkmcnt(6)
	v_mfma_f32_16x16x32_bf16 v[40:43], v[100:103], v[104:107], v[40:43]
	v_mfma_f32_16x16x32_bf16 v[44:47], v[100:103], v[118:121], v[44:47]
	s_waitcnt lgkmcnt(5)
	v_mfma_f32_16x16x32_bf16 v[48:51], v[114:117], v[104:107], v[48:51]
	v_mfma_f32_16x16x32_bf16 v[52:55], v[114:117], v[118:121], v[52:55]
	s_waitcnt lgkmcnt(4)
	v_mfma_f32_16x16x32_bf16 v[56:59], v[142:145], v[104:107], v[56:59]
	v_mfma_f32_16x16x32_bf16 v[60:63], v[142:145], v[118:121], v[60:63]
	s_waitcnt lgkmcnt(3)
	v_mfma_f32_16x16x32_bf16 v[64:67], v[146:149], v[104:107], v[64:67]
	v_mfma_f32_16x16x32_bf16 v[68:71], v[146:149], v[118:121], v[68:71]
	s_waitcnt lgkmcnt(2)
	v_mfma_f32_16x16x32_bf16 v[72:75], v[150:153], v[104:107], v[72:75]
	v_mfma_f32_16x16x32_bf16 v[76:79], v[150:153], v[118:121], v[76:79]
	s_waitcnt lgkmcnt(1)
	v_mfma_f32_16x16x32_bf16 v[80:83], v[158:161], v[104:107], v[80:83]
	v_mfma_f32_16x16x32_bf16 v[84:87], v[158:161], v[118:121], v[84:87]
	s_waitcnt lgkmcnt(0)
	v_mfma_f32_16x16x32_bf16 v[88:91], v[188:191], v[104:107], v[88:91]
	v_mfma_f32_16x16x32_bf16 v[92:95], v[188:191], v[118:121], v[92:95]
	s_setprio 0
	ds_read_b128 v[96:99], v157 offset:128
	ds_read_b128 v[100:103], v157 offset:4480
	ds_read_b128 v[104:107], v157 offset:8832
	ds_read_b128 v[114:117], v157 offset:13184
	ds_read_b128 v[118:121], v157 offset:17536
	ds_read_b128 v[142:145], v157 offset:21888
	ds_read_b128 v[146:149], v157 offset:26240
	ds_read_b128 v[150:153], v157 offset:30592
	s_setprio 1
	s_waitcnt lgkmcnt(7)
	v_mfma_f32_16x16x32_bf16 v[32:35], v[96:99], v[122:125], v[32:35]
	v_mfma_f32_16x16x32_bf16 v[36:39], v[96:99], v[130:133], v[36:39]
	s_waitcnt lgkmcnt(6)
	v_mfma_f32_16x16x32_bf16 v[40:43], v[100:103], v[122:125], v[40:43]
	v_mfma_f32_16x16x32_bf16 v[44:47], v[100:103], v[130:133], v[44:47]
	s_waitcnt lgkmcnt(5)
	v_mfma_f32_16x16x32_bf16 v[48:51], v[104:107], v[122:125], v[48:51]
	v_mfma_f32_16x16x32_bf16 v[52:55], v[104:107], v[130:133], v[52:55]
	s_waitcnt lgkmcnt(4)
	v_mfma_f32_16x16x32_bf16 v[56:59], v[114:117], v[122:125], v[56:59]
	v_mfma_f32_16x16x32_bf16 v[60:63], v[114:117], v[130:133], v[60:63]
	s_waitcnt lgkmcnt(3)
	v_mfma_f32_16x16x32_bf16 v[64:67], v[118:121], v[122:125], v[64:67]
	v_mfma_f32_16x16x32_bf16 v[68:71], v[118:121], v[130:133], v[68:71]
	s_waitcnt lgkmcnt(2)
	v_mfma_f32_16x16x32_bf16 v[72:75], v[142:145], v[122:125], v[72:75]
	v_mfma_f32_16x16x32_bf16 v[76:79], v[142:145], v[130:133], v[76:79]
	s_waitcnt lgkmcnt(1)
	v_mfma_f32_16x16x32_bf16 v[80:83], v[146:149], v[122:125], v[80:83]
	v_mfma_f32_16x16x32_bf16 v[84:87], v[146:149], v[130:133], v[84:87]
	s_waitcnt lgkmcnt(0)
	v_mfma_f32_16x16x32_bf16 v[88:91], v[150:153], v[122:125], v[88:91]
	v_mfma_f32_16x16x32_bf16 v[92:95], v[150:153], v[130:133], v[92:95]
	s_setprio 0
	ds_read_b128 v[96:99], v157 offset:192
	ds_read_b128 v[100:103], v157 offset:4544
	ds_read_b128 v[104:107], v157 offset:8896
	ds_read_b128 v[114:117], v157 offset:13248
	ds_read_b128 v[118:121], v157 offset:17600
	ds_read_b128 v[122:125], v157 offset:21952
	ds_read_b128 v[130:133], v157 offset:26304
	ds_read_b128 v[142:145], v157 offset:30656
	s_setprio 1
	s_waitcnt lgkmcnt(7)
	v_mfma_f32_16x16x32_bf16 v[32:35], v[96:99], v[134:137], v[32:35]
	v_mfma_f32_16x16x32_bf16 v[36:39], v[96:99], v[138:141], v[36:39]
	s_waitcnt lgkmcnt(6)
	v_mfma_f32_16x16x32_bf16 v[40:43], v[100:103], v[134:137], v[40:43]
	v_mfma_f32_16x16x32_bf16 v[44:47], v[100:103], v[138:141], v[44:47]
	s_waitcnt lgkmcnt(5)
	v_mfma_f32_16x16x32_bf16 v[48:51], v[104:107], v[134:137], v[48:51]
	v_mfma_f32_16x16x32_bf16 v[52:55], v[104:107], v[138:141], v[52:55]
	s_waitcnt lgkmcnt(4)
	v_mfma_f32_16x16x32_bf16 v[56:59], v[114:117], v[134:137], v[56:59]
	v_mfma_f32_16x16x32_bf16 v[60:63], v[114:117], v[138:141], v[60:63]
	s_waitcnt lgkmcnt(3)
	v_mfma_f32_16x16x32_bf16 v[64:67], v[118:121], v[134:137], v[64:67]
	v_mfma_f32_16x16x32_bf16 v[68:71], v[118:121], v[138:141], v[68:71]
	s_waitcnt lgkmcnt(2)
	v_mfma_f32_16x16x32_bf16 v[72:75], v[122:125], v[134:137], v[72:75]
	v_mfma_f32_16x16x32_bf16 v[76:79], v[122:125], v[138:141], v[76:79]
	s_waitcnt lgkmcnt(1)
	v_mfma_f32_16x16x32_bf16 v[80:83], v[130:133], v[134:137], v[80:83]
	v_mfma_f32_16x16x32_bf16 v[84:87], v[130:133], v[138:141], v[84:87]
	s_waitcnt lgkmcnt(0)
	v_mfma_f32_16x16x32_bf16 v[88:91], v[142:145], v[134:137], v[88:91]
	v_mfma_f32_16x16x32_bf16 v[92:95], v[142:145], v[138:141], v[92:95]
	s_setprio 0
	s_nop 0
	v_lshlrev_b32_e32 v96, 16, v28
	v_and_b32_e32 v97, 0xffff0000, v28
	v_pk_mul_f32 v[96:97], v[112:113], v[96:97] op_sel_hi:[0,1]
	v_cvt_pk_bf16_f32 v28, v96, v97
	v_lshlrev_b32_e32 v96, 16, v29
	v_and_b32_e32 v97, 0xffff0000, v29
	v_pk_mul_f32 v[96:97], v[112:113], v[96:97] op_sel_hi:[0,1]
	v_cvt_pk_bf16_f32 v29, v96, v97
	v_lshlrev_b32_e32 v96, 16, v30
	v_and_b32_e32 v97, 0xffff0000, v30
	v_pk_mul_f32 v[96:97], v[112:113], v[96:97] op_sel_hi:[0,1]
	v_cvt_pk_bf16_f32 v30, v96, v97
	v_lshlrev_b32_e32 v96, 16, v31
	v_and_b32_e32 v97, 0xffff0000, v31
	v_pk_mul_f32 v[96:97], v[112:113], v[96:97] op_sel_hi:[0,1]
	v_cvt_pk_bf16_f32 v31, v96, v97
	v_lshlrev_b32_e32 v96, 16, v24
	v_and_b32_e32 v97, 0xffff0000, v24
	v_pk_mul_f32 v[96:97], v[110:111], v[96:97] op_sel_hi:[0,1]
	v_cvt_pk_bf16_f32 v24, v96, v97
	v_lshlrev_b32_e32 v96, 16, v25
	v_and_b32_e32 v97, 0xffff0000, v25
	v_pk_mul_f32 v[96:97], v[110:111], v[96:97] op_sel_hi:[0,1]
	v_cvt_pk_bf16_f32 v25, v96, v97
	v_lshlrev_b32_e32 v96, 16, v26
	v_and_b32_e32 v97, 0xffff0000, v26
	v_pk_mul_f32 v[96:97], v[110:111], v[96:97] op_sel_hi:[0,1]
	v_cvt_pk_bf16_f32 v26, v96, v97
	v_lshlrev_b32_e32 v96, 16, v27
	v_and_b32_e32 v97, 0xffff0000, v27
	v_pk_mul_f32 v[96:97], v[110:111], v[96:97] op_sel_hi:[0,1]
	v_cvt_pk_bf16_f32 v27, v96, v97
	v_lshlrev_b32_e32 v96, 16, v20
	v_and_b32_e32 v97, 0xffff0000, v20
	v_pk_mul_f32 v[96:97], v[112:113], v[96:97] op_sel_hi:[0,1]
	v_cvt_pk_bf16_f32 v20, v96, v97
	v_lshlrev_b32_e32 v96, 16, v21
	v_and_b32_e32 v97, 0xffff0000, v21
	v_pk_mul_f32 v[96:97], v[112:113], v[96:97] op_sel_hi:[0,1]
	v_cvt_pk_bf16_f32 v21, v96, v97
	v_lshlrev_b32_e32 v96, 16, v22
	v_and_b32_e32 v97, 0xffff0000, v22
	v_pk_mul_f32 v[96:97], v[112:113], v[96:97] op_sel_hi:[0,1]
	v_cvt_pk_bf16_f32 v22, v96, v97
	v_lshlrev_b32_e32 v96, 16, v23
	v_and_b32_e32 v97, 0xffff0000, v23
	v_pk_mul_f32 v[96:97], v[112:113], v[96:97] op_sel_hi:[0,1]
	v_cvt_pk_bf16_f32 v23, v96, v97
	v_lshlrev_b32_e32 v96, 16, v16
	v_and_b32_e32 v97, 0xffff0000, v16
	v_pk_mul_f32 v[96:97], v[110:111], v[96:97] op_sel_hi:[0,1]
	v_cvt_pk_bf16_f32 v16, v96, v97
	v_lshlrev_b32_e32 v96, 16, v17
	v_and_b32_e32 v97, 0xffff0000, v17
	v_pk_mul_f32 v[96:97], v[110:111], v[96:97] op_sel_hi:[0,1]
	v_cvt_pk_bf16_f32 v17, v96, v97
	v_lshlrev_b32_e32 v96, 16, v18
	v_and_b32_e32 v97, 0xffff0000, v18
	v_pk_mul_f32 v[96:97], v[110:111], v[96:97] op_sel_hi:[0,1]
	v_cvt_pk_bf16_f32 v18, v96, v97
	v_lshlrev_b32_e32 v96, 16, v19
	v_and_b32_e32 v97, 0xffff0000, v19
	v_pk_mul_f32 v[96:97], v[110:111], v[96:97] op_sel_hi:[0,1]
	v_cvt_pk_bf16_f32 v19, v96, v97
	v_lshlrev_b32_e32 v96, 16, v12
	v_and_b32_e32 v97, 0xffff0000, v12
	v_pk_mul_f32 v[96:97], v[112:113], v[96:97] op_sel_hi:[0,1]
	v_cvt_pk_bf16_f32 v12, v96, v97
	v_lshlrev_b32_e32 v96, 16, v13
	v_and_b32_e32 v97, 0xffff0000, v13
	v_pk_mul_f32 v[96:97], v[112:113], v[96:97] op_sel_hi:[0,1]
	v_cvt_pk_bf16_f32 v13, v96, v97
	v_lshlrev_b32_e32 v96, 16, v14
	v_and_b32_e32 v97, 0xffff0000, v14
	v_pk_mul_f32 v[96:97], v[112:113], v[96:97] op_sel_hi:[0,1]
	v_cvt_pk_bf16_f32 v14, v96, v97
	v_lshlrev_b32_e32 v96, 16, v15
	v_and_b32_e32 v97, 0xffff0000, v15
	v_pk_mul_f32 v[96:97], v[112:113], v[96:97] op_sel_hi:[0,1]
	v_cvt_pk_bf16_f32 v15, v96, v97
	v_lshlrev_b32_e32 v96, 16, v8
	v_and_b32_e32 v97, 0xffff0000, v8
	v_pk_mul_f32 v[96:97], v[110:111], v[96:97] op_sel_hi:[0,1]
	v_cvt_pk_bf16_f32 v8, v96, v97
	v_lshlrev_b32_e32 v96, 16, v9
	v_and_b32_e32 v97, 0xffff0000, v9
	v_pk_mul_f32 v[96:97], v[110:111], v[96:97] op_sel_hi:[0,1]
	v_cvt_pk_bf16_f32 v9, v96, v97
	v_lshlrev_b32_e32 v96, 16, v10
	v_and_b32_e32 v97, 0xffff0000, v10
	v_pk_mul_f32 v[96:97], v[110:111], v[96:97] op_sel_hi:[0,1]
	v_cvt_pk_bf16_f32 v10, v96, v97
	v_lshlrev_b32_e32 v96, 16, v11
	v_and_b32_e32 v97, 0xffff0000, v11
	v_pk_mul_f32 v[96:97], v[110:111], v[96:97] op_sel_hi:[0,1]
	v_cvt_pk_bf16_f32 v11, v96, v97
	v_lshlrev_b32_e32 v96, 16, v4
	v_and_b32_e32 v97, 0xffff0000, v4
	v_lshlrev_b32_e32 v4, 16, v5
	v_and_b32_e32 v5, 0xffff0000, v5
	v_pk_mul_f32 v[96:97], v[112:113], v[96:97] op_sel_hi:[0,1]
	v_pk_mul_f32 v[4:5], v[112:113], v[4:5] op_sel_hi:[0,1]
	v_cvt_pk_bf16_f32 v96, v96, v97
	v_cvt_pk_bf16_f32 v97, v4, v5
	v_lshlrev_b32_e32 v4, 16, v6
	v_and_b32_e32 v5, 0xffff0000, v6
	v_pk_mul_f32 v[4:5], v[112:113], v[4:5] op_sel_hi:[0,1]
	v_cvt_pk_bf16_f32 v98, v4, v5
	v_lshlrev_b32_e32 v4, 16, v7
	v_and_b32_e32 v5, 0xffff0000, v7
	v_pk_mul_f32 v[4:5], v[112:113], v[4:5] op_sel_hi:[0,1]
	v_cvt_pk_bf16_f32 v99, v4, v5
	s_nop 0
	v_lshlrev_b32_e32 v4, 16, v0
	v_and_b32_e32 v5, 0xffff0000, v0
	v_pk_mul_f32 v[4:5], v[110:111], v[4:5] op_sel_hi:[0,1]
	v_cvt_pk_bf16_f32 v0, v4, v5
	v_lshlrev_b32_e32 v4, 16, v1
	v_and_b32_e32 v5, 0xffff0000, v1
	v_pk_mul_f32 v[4:5], v[110:111], v[4:5] op_sel_hi:[0,1]
	v_cvt_pk_bf16_f32 v1, v4, v5
	v_lshlrev_b32_e32 v4, 16, v2
	v_and_b32_e32 v5, 0xffff0000, v2
	v_pk_mul_f32 v[4:5], v[110:111], v[4:5] op_sel_hi:[0,1]
	v_cvt_pk_bf16_f32 v2, v4, v5
	v_lshlrev_b32_e32 v4, 16, v3
	v_and_b32_e32 v5, 0xffff0000, v3
	v_pk_mul_f32 v[4:5], v[110:111], v[4:5] op_sel_hi:[0,1]
	v_cvt_pk_bf16_f32 v3, v4, v5
	ds_read_b128 v[4:7], v157 offset:34816
	ds_read_b128 v[100:103], v157 offset:39168
	ds_read_b128 v[104:107], v157 offset:43520
	ds_read_b128 v[110:113], v157 offset:47872
	ds_read_b128 v[114:117], v157 offset:52224
	ds_read_b128 v[118:121], v157 offset:56576
	ds_read_b128 v[122:125], v157 offset:60928
	ds_read_b128 v[130:133], v157 offset:65280
	s_setprio 1
	s_waitcnt lgkmcnt(7)
	v_mfma_f32_16x16x32_bf16 v[32:35], v[4:7], v[28:31], v[32:35]
	v_mfma_f32_16x16x32_bf16 v[4:7], v[4:7], v[24:27], v[36:39]
	s_waitcnt lgkmcnt(6)
	v_mfma_f32_16x16x32_bf16 v[36:39], v[100:103], v[28:31], v[40:43]
	v_mfma_f32_16x16x32_bf16 v[40:43], v[100:103], v[24:27], v[44:47]
	s_waitcnt lgkmcnt(5)
	v_mfma_f32_16x16x32_bf16 v[44:47], v[104:107], v[28:31], v[48:51]
	v_mfma_f32_16x16x32_bf16 v[48:51], v[104:107], v[24:27], v[52:55]
	s_waitcnt lgkmcnt(4)
	v_mfma_f32_16x16x32_bf16 v[52:55], v[110:113], v[28:31], v[56:59]
	v_mfma_f32_16x16x32_bf16 v[56:59], v[110:113], v[24:27], v[60:63]
	s_waitcnt lgkmcnt(3)
	v_mfma_f32_16x16x32_bf16 v[60:63], v[114:117], v[28:31], v[64:67]
	v_mfma_f32_16x16x32_bf16 v[64:67], v[114:117], v[24:27], v[68:71]
	s_waitcnt lgkmcnt(2)
	v_mfma_f32_16x16x32_bf16 v[68:71], v[118:121], v[28:31], v[72:75]
	v_mfma_f32_16x16x32_bf16 v[72:75], v[118:121], v[24:27], v[76:79]
	s_waitcnt lgkmcnt(1)
	v_mfma_f32_16x16x32_bf16 v[76:79], v[122:125], v[28:31], v[80:83]
	v_mfma_f32_16x16x32_bf16 v[80:83], v[122:125], v[24:27], v[84:87]
	s_waitcnt lgkmcnt(0)
	v_mfma_f32_16x16x32_bf16 v[28:31], v[130:133], v[28:31], v[88:91]
	v_mfma_f32_16x16x32_bf16 v[24:27], v[130:133], v[24:27], v[92:95]
	s_setprio 0
	ds_read_b128 v[84:87], v157 offset:34880
	ds_read_b128 v[88:91], v157 offset:39232
	ds_read_b128 v[92:95], v157 offset:43584
	ds_read_b128 v[100:103], v157 offset:47936
	ds_read_b128 v[104:107], v157 offset:52288
	ds_read_b128 v[110:113], v157 offset:56640
	ds_read_b128 v[114:117], v157 offset:60992
	ds_read_b128 v[118:121], v157 offset:65344
	s_setprio 1
	s_waitcnt lgkmcnt(7)
	v_mfma_f32_16x16x32_bf16 v[32:35], v[84:87], v[20:23], v[32:35]
	v_mfma_f32_16x16x32_bf16 v[4:7], v[84:87], v[16:19], v[4:7]
	s_waitcnt lgkmcnt(6)
	v_mfma_f32_16x16x32_bf16 v[36:39], v[88:91], v[20:23], v[36:39]
	v_mfma_f32_16x16x32_bf16 v[40:43], v[88:91], v[16:19], v[40:43]
	s_waitcnt lgkmcnt(5)
	v_mfma_f32_16x16x32_bf16 v[44:47], v[92:95], v[20:23], v[44:47]
	v_mfma_f32_16x16x32_bf16 v[48:51], v[92:95], v[16:19], v[48:51]
	s_waitcnt lgkmcnt(4)
	v_mfma_f32_16x16x32_bf16 v[52:55], v[100:103], v[20:23], v[52:55]
	v_mfma_f32_16x16x32_bf16 v[56:59], v[100:103], v[16:19], v[56:59]
	s_waitcnt lgkmcnt(3)
	v_mfma_f32_16x16x32_bf16 v[60:63], v[104:107], v[20:23], v[60:63]
	v_mfma_f32_16x16x32_bf16 v[64:67], v[104:107], v[16:19], v[64:67]
	s_waitcnt lgkmcnt(2)
	v_mfma_f32_16x16x32_bf16 v[68:71], v[110:113], v[20:23], v[68:71]
	v_mfma_f32_16x16x32_bf16 v[72:75], v[110:113], v[16:19], v[72:75]
	s_waitcnt lgkmcnt(1)
	v_mfma_f32_16x16x32_bf16 v[76:79], v[114:117], v[20:23], v[76:79]
	v_mfma_f32_16x16x32_bf16 v[80:83], v[114:117], v[16:19], v[80:83]
	s_waitcnt lgkmcnt(0)
	v_mfma_f32_16x16x32_bf16 v[20:23], v[118:121], v[20:23], v[28:31]
	v_mfma_f32_16x16x32_bf16 v[16:19], v[118:121], v[16:19], v[24:27]
	s_setprio 0
	s_nop 1
	ds_read_b128 v[24:27], v157 offset:34944
	ds_read_b128 v[28:31], v157 offset:39296
	ds_read_b128 v[84:87], v157 offset:43648
	ds_read_b128 v[88:91], v157 offset:48000
	ds_read_b128 v[92:95], v157 offset:52352
	ds_read_b128 v[100:103], v157 offset:56704
	ds_read_b128 v[104:107], v157 offset:61056
	ds_read_b128 v[110:113], v157 offset:65408
	s_setprio 1
	s_waitcnt lgkmcnt(7)
	v_mfma_f32_16x16x32_bf16 v[32:35], v[24:27], v[12:15], v[32:35]
	v_mfma_f32_16x16x32_bf16 v[4:7], v[24:27], v[8:11], v[4:7]
	s_waitcnt lgkmcnt(6)
	v_mfma_f32_16x16x32_bf16 v[24:27], v[28:31], v[12:15], v[36:39]
	v_mfma_f32_16x16x32_bf16 v[36:39], v[28:31], v[8:11], v[40:43]
	s_waitcnt lgkmcnt(5)
	v_mfma_f32_16x16x32_bf16 v[40:43], v[84:87], v[12:15], v[44:47]
	v_mfma_f32_16x16x32_bf16 v[44:47], v[84:87], v[8:11], v[48:51]
	s_waitcnt lgkmcnt(4)
	v_mfma_f32_16x16x32_bf16 v[48:51], v[88:91], v[12:15], v[52:55]
	v_mfma_f32_16x16x32_bf16 v[84:87], v[88:91], v[8:11], v[56:59]
	s_waitcnt lgkmcnt(3)
	v_mfma_f32_16x16x32_bf16 v[88:91], v[92:95], v[12:15], v[60:63]
	v_mfma_f32_16x16x32_bf16 v[64:67], v[92:95], v[8:11], v[64:67]
	s_waitcnt lgkmcnt(2)
	v_mfma_f32_16x16x32_bf16 v[68:71], v[100:103], v[12:15], v[68:71]
	v_mfma_f32_16x16x32_bf16 v[72:75], v[100:103], v[8:11], v[72:75]
	s_waitcnt lgkmcnt(1)
	v_mfma_f32_16x16x32_bf16 v[76:79], v[104:107], v[12:15], v[76:79]
	v_mfma_f32_16x16x32_bf16 v[80:83], v[104:107], v[8:11], v[80:83]
	s_waitcnt lgkmcnt(0)
	v_mfma_f32_16x16x32_bf16 v[92:95], v[110:113], v[12:15], v[20:23]
	v_mfma_f32_16x16x32_bf16 v[100:103], v[110:113], v[8:11], v[16:19]
	s_setprio 0
	ds_read_b128 v[8:11], v157 offset:35008
	ds_read_b128 v[12:15], v157 offset:39360
	ds_read_b128 v[16:19], v157 offset:43712
	ds_read_b128 v[104:107], v157 offset:48064
	ds_read_b128 v[110:113], v157 offset:52416
	ds_read_b128 v[114:117], v157 offset:56768
	ds_read_b128 v[118:121], v157 offset:61120
	ds_read_b128 v[122:125], v157 offset:65472
	s_setprio 1
	s_waitcnt lgkmcnt(7)
	v_mfma_f32_16x16x32_bf16 v[60:63], v[8:11], v[96:99], v[32:35]
	v_mfma_f32_16x16x32_bf16 v[28:31], v[8:11], v[0:3], v[4:7]
	s_waitcnt lgkmcnt(6)
	v_mfma_f32_16x16x32_bf16 v[56:59], v[12:15], v[96:99], v[24:27]
	v_mfma_f32_16x16x32_bf16 v[24:27], v[12:15], v[0:3], v[36:39]
	s_waitcnt lgkmcnt(5)
	v_mfma_f32_16x16x32_bf16 v[52:55], v[16:19], v[96:99], v[40:43]
	v_mfma_f32_16x16x32_bf16 v[20:23], v[16:19], v[0:3], v[44:47]
	s_waitcnt lgkmcnt(4)
	v_mfma_f32_16x16x32_bf16 v[48:51], v[104:107], v[96:99], v[48:51]
	v_mfma_f32_16x16x32_bf16 v[16:19], v[104:107], v[0:3], v[84:87]
	s_waitcnt lgkmcnt(3)
	v_mfma_f32_16x16x32_bf16 v[44:47], v[110:113], v[96:99], v[88:91]
	v_mfma_f32_16x16x32_bf16 v[12:15], v[110:113], v[0:3], v[64:67]
	s_waitcnt lgkmcnt(2)
	v_mfma_f32_16x16x32_bf16 v[40:43], v[114:117], v[96:99], v[68:71]
	v_mfma_f32_16x16x32_bf16 v[8:11], v[114:117], v[0:3], v[72:75]
	s_waitcnt lgkmcnt(1)
	v_mfma_f32_16x16x32_bf16 v[36:39], v[118:121], v[96:99], v[76:79]
	v_mfma_f32_16x16x32_bf16 v[4:7], v[118:121], v[0:3], v[80:83]
	s_waitcnt lgkmcnt(0)
	v_mfma_f32_16x16x32_bf16 v[32:35], v[122:125], v[96:99], v[92:95]
	v_mfma_f32_16x16x32_bf16 v[0:3], v[122:125], v[0:3], v[100:103]
	s_setprio 0
	v_mov_b32_e32 v64, v60
	v_mov_b32_e32 v65, v56
	v_mov_b32_e32 v66, v61
	v_mov_b32_e32 v67, v57
	v_pk_add_f32 v[64:65], v[64:65], v[66:67]
	v_mov_b32_e32 v66, v62
	v_mov_b32_e32 v67, v58
	v_pk_add_f32 v[64:65], v[66:67], v[64:65]
	v_mov_b32_e32 v66, v63
	v_mov_b32_e32 v67, v59
	v_pk_add_f32 v[64:65], v[66:67], v[64:65]
	v_mov_b32_e32 v66, v53
	v_add_f32_e32 v64, 0, v64
	v_add_f32_e32 v68, v64, v65
	v_mov_b32_e32 v64, v52
	v_mov_b32_e32 v65, v48
	v_mov_b32_e32 v67, v49
	v_pk_add_f32 v[64:65], v[64:65], v[66:67]
	v_mov_b32_e32 v66, v54
	v_mov_b32_e32 v67, v50
	v_pk_add_f32 v[64:65], v[66:67], v[64:65]
	v_mov_b32_e32 v66, v55
	v_mov_b32_e32 v67, v51
	v_pk_add_f32 v[64:65], v[66:67], v[64:65]
	v_mov_b32_e32 v66, v45
	v_add_f32_e32 v64, v68, v64
	v_add_f32_e32 v68, v64, v65
	v_mov_b32_e32 v64, v44
	v_mov_b32_e32 v65, v40
	v_mov_b32_e32 v67, v41
	v_pk_add_f32 v[64:65], v[64:65], v[66:67]
	v_mov_b32_e32 v66, v46
	v_mov_b32_e32 v67, v42
	v_pk_add_f32 v[64:65], v[66:67], v[64:65]
	v_mov_b32_e32 v66, v47
	v_mov_b32_e32 v67, v43
	v_pk_add_f32 v[64:65], v[66:67], v[64:65]
	v_mov_b32_e32 v66, v37
	v_add_f32_e32 v64, v68, v64
	v_add_f32_e32 v68, v64, v65
	v_mov_b32_e32 v64, v36
	v_mov_b32_e32 v65, v32
	v_mov_b32_e32 v67, v33
	v_pk_add_f32 v[64:65], v[64:65], v[66:67]
	v_mov_b32_e32 v66, v38
	v_mov_b32_e32 v67, v34
	v_pk_add_f32 v[64:65], v[66:67], v[64:65]
	v_mov_b32_e32 v66, v39
	v_mov_b32_e32 v67, v35
	v_pk_add_f32 v[64:65], v[66:67], v[64:65]
	s_load_dwordx16 s[40:55], s[0:1], 0x100
	v_add_f32_e32 v64, v68, v64
	v_add_f32_e32 v64, v64, v65
	ds_bpermute_b32 v65, v109, v64
	s_lshl_b32 s2, s57, 2
	v_readlane_b32 s4, v241, 38
	s_add_u32 s30, s4, s2
	v_readlane_b32 s2, v241, 39
	s_waitcnt lgkmcnt(0)
	v_add_f32_e32 v65, v64, v65
	ds_bpermute_b32 v66, v154, v65
	v_add_u32_e32 v64, s66, v108
	s_addc_u32 s31, s2, 0
	s_lshl_b32 s96, s57, 1
	v_lshlrev_b32_e32 v128, 1, v156
	s_waitcnt lgkmcnt(0)
	v_add_f32_e32 v69, v65, v66
	v_ashrrev_i32_e32 v65, 31, v64
	v_lshlrev_b64 v[66:67], 14, v[64:65]
	v_lshl_add_u64 v[66:67], s[52:53], 0, v[66:67]
	v_lshl_add_u64 v[66:67], v[66:67], 0, s[96:97]
	v_lshl_add_u64 v[78:79], v[66:67], 0, v[128:129]
	s_movk_i32 s38, 0x1000
	v_add_co_u32_e32 v66, vcc, s38, v78
	v_lshlrev_b32_e32 v68, 2, v156
	s_nop 0
	v_addc_co_u32_e32 v67, vcc, 0, v79, vcc
	global_load_dwordx2 v[80:81], v[66:67], off offset:2048
	global_load_dwordx4 v[70:73], v68, s[30:31]
	v_fmamk_f32 v77, v69, 0xbc000000, v61
	v_fmamk_f32 v76, v69, 0xbc000000, v60
	v_mul_f32_e32 v75, v77, v77
	v_fmac_f32_e32 v75, v76, v76
	v_fmamk_f32 v62, v69, 0xbc000000, v62
	v_fmac_f32_e32 v75, v62, v62
	v_fmac_f32_e32 v63, 0xbc000000, v69
	v_fmac_f32_e32 v75, v63, v63
	v_fmamk_f32 v60, v69, 0xbc000000, v56
	v_fmac_f32_e32 v75, v60, v60
	v_fmamk_f32 v61, v69, 0xbc000000, v57
	v_fmac_f32_e32 v75, v61, v61
	v_fmamk_f32 v58, v69, 0xbc000000, v58
	v_fmac_f32_e32 v75, v58, v58
	v_fmac_f32_e32 v59, 0xbc000000, v69
	v_fmac_f32_e32 v75, v59, v59
	v_fmamk_f32 v82, v69, 0xbc000000, v52
	v_fmac_f32_e32 v75, v82, v82
	v_fmamk_f32 v83, v69, 0xbc000000, v53
	v_fmac_f32_e32 v75, v83, v83
	v_fmamk_f32 v54, v69, 0xbc000000, v54
	v_fmac_f32_e32 v75, v54, v54
	v_fmac_f32_e32 v55, 0xbc000000, v69
	v_fmac_f32_e32 v75, v55, v55
	v_fmamk_f32 v66, v69, 0xbc000000, v48
	v_fmac_f32_e32 v75, v66, v66
	v_fmamk_f32 v67, v69, 0xbc000000, v49
	v_fmac_f32_e32 v75, v67, v67
	v_fmamk_f32 v50, v69, 0xbc000000, v50
	v_fmac_f32_e32 v75, v50, v50
	v_fmac_f32_e32 v51, 0xbc000000, v69
	v_fmac_f32_e32 v75, v51, v51
	v_fmamk_f32 v56, v69, 0xbc000000, v44
	v_fmac_f32_e32 v75, v56, v56
	v_fmamk_f32 v57, v69, 0xbc000000, v45
	v_fmac_f32_e32 v75, v57, v57
	v_fmamk_f32 v46, v69, 0xbc000000, v46
	v_fmac_f32_e32 v75, v46, v46
	v_fmac_f32_e32 v47, 0xbc000000, v69
	v_fmac_f32_e32 v75, v47, v47
	v_fmamk_f32 v52, v69, 0xbc000000, v40
	v_fmac_f32_e32 v75, v52, v52
	v_fmamk_f32 v53, v69, 0xbc000000, v41
	v_fmac_f32_e32 v75, v53, v53
	v_fmamk_f32 v42, v69, 0xbc000000, v42
	v_fmac_f32_e32 v75, v42, v42
	v_fmac_f32_e32 v43, 0xbc000000, v69
	v_mul_f32_e32 v74, 0x3c000000, v69
	v_fmac_f32_e32 v75, v43, v43
	v_pk_add_f32 v[40:41], v[36:37], v[74:75] op_sel_hi:[1,0] neg_lo:[0,1] neg_hi:[0,1]
	s_mov_b32 s2, 0x800000
	v_pk_mul_f32 v[40:41], v[40:41], v[40:41]
	s_load_dwordx16 s[4:19], s[0:1], 0x140
	v_add_f32_e32 v40, v40, v75
	v_add_f32_e32 v44, v41, v40
	v_pk_add_f32 v[40:41], v[38:39], v[74:75] op_sel_hi:[1,0] neg_lo:[0,1] neg_hi:[0,1]
	s_mov_b64 s[40:41], 0x1800
	v_pk_mul_f32 v[40:41], v[40:41], v[40:41]
	v_fmamk_f32 v37, v69, 0xbc000000, v37
	v_add_f32_e32 v40, v40, v44
	v_add_f32_e32 v44, v41, v40
	v_pk_add_f32 v[40:41], v[32:33], v[74:75] op_sel_hi:[1,0] neg_lo:[0,1] neg_hi:[0,1]
	v_fmamk_f32 v36, v69, 0xbc000000, v36
	v_pk_mul_f32 v[40:41], v[40:41], v[40:41]
	v_fmamk_f32 v39, v69, 0xbc000000, v39
	v_add_f32_e32 v40, v40, v44
	v_add_f32_e32 v44, v41, v40
	v_pk_add_f32 v[40:41], v[34:35], v[74:75] op_sel_hi:[1,0] neg_lo:[0,1] neg_hi:[0,1]
	v_fmac_f32_e32 v38, 0xbc000000, v69
	v_pk_mul_f32 v[40:41], v[40:41], v[40:41]
	v_fmamk_f32 v33, v69, 0xbc000000, v33
	v_add_f32_e32 v40, v40, v44
	v_add_f32_e32 v40, v41, v40
	ds_bpermute_b32 v41, v109, v40
	v_fmamk_f32 v32, v69, 0xbc000000, v32
	v_fmamk_f32 v35, v69, 0xbc000000, v35
	v_fmac_f32_e32 v34, 0xbc000000, v69
	s_add_i32 s70, s70, s64
	s_waitcnt lgkmcnt(0)
	v_add_f32_e32 v40, v40, v41
	ds_bpermute_b32 v41, v154, v40
	s_waitcnt vmcnt(1)
	v_and_b32_e32 v45, 0xffff0000, v80
	v_lshlrev_b32_e32 v48, 16, v81
	v_and_b32_e32 v49, 0xffff0000, v81
	s_cmpk_gt_i32 s70, 0x41f
	s_waitcnt lgkmcnt(0)
	v_add_f32_e32 v40, v40, v41
	v_fmamk_f32 v40, v40, 0x3c000000, v163
	v_mul_f32_e32 v41, 0x4b800000, v40
	v_cmp_gt_f32_e32 vcc, s2, v40
	s_nop 1
	v_cndmask_b32_e32 v40, v40, v41, vcc
	v_rsq_f32_e32 v40, v40
	s_nop 0
	v_mul_f32_e32 v41, 0x45800000, v40
	v_cndmask_b32_e32 v40, v40, v41, vcc
	v_lshlrev_b32_e32 v41, 16, v80
	v_mul_f32_e32 v41, 0xbfb8aa3b, v41
	v_exp_f32_e32 v41, v41
	v_lshlrev_b64 v[80:81], 11, v[64:65]
	v_add_f32_e32 v41, 1.0, v41
	v_rcp_f32_e32 v44, v41
	v_mul_f32_e32 v41, 0xbfb8aa3b, v45
	v_mul_f32_e32 v45, 0xbfb8aa3b, v48
	v_exp_f32_e32 v45, v45
	v_mul_f32_e32 v48, 0xbfb8aa3b, v49
	v_exp_f32_e32 v41, v41
	v_exp_f32_e32 v48, v48
	v_add_f32_e32 v45, 1.0, v45
	v_rcp_f32_e32 v74, v45
	v_add_f32_e32 v41, 1.0, v41
	v_add_f32_e32 v45, 1.0, v48
	v_rcp_f32_e32 v75, v45
	v_rcp_f32_e32 v45, v41
	v_lshl_add_u64 v[48:49], v[78:79], 0, s[40:41]
	global_load_dwordx2 v[204:205], v[48:49], off offset:32
	global_load_dwordx2 v[206:207], v[48:49], off offset:64
	global_load_dwordx2 v[208:209], v[48:49], off offset:96
	global_load_dwordx2 v[210:211], v[48:49], off offset:128
	global_load_dwordx2 v[216:217], v[48:49], off offset:160
	global_load_dwordx2 v[218:219], v[48:49], off offset:192
	global_load_dwordx2 v[220:221], v[48:49], off offset:224
	global_load_dwordx4 v[224:227], v68, s[30:31] offset:64
	global_load_dwordx4 v[228:231], v68, s[30:31] offset:128
	global_load_dwordx4 v[232:235], v68, s[30:31] offset:192
	global_load_dwordx4 v[236:239], v68, s[30:31] offset:256
	v_mov_b32_e32 v78, v6
	v_pk_mul_f32 v[62:63], v[62:63], v[74:75]
	v_pk_mul_f32 v[44:45], v[76:77], v[44:45]
	v_pk_mul_f32 v[62:63], v[62:63], v[40:41] op_sel_hi:[1,0]
	v_pk_mul_f32 v[44:45], v[44:45], v[40:41] op_sel_hi:[1,0]
	s_waitcnt vmcnt(0)
	v_pk_mul_f32 v[62:63], v[72:73], v[62:63]
	v_pk_mul_f32 v[44:45], v[70:71], v[44:45]
	v_cvt_pk_bf16_f32 v71, v62, v63
	v_cvt_pk_bf16_f32 v70, v44, v45
	v_lshl_add_u64 v[44:45], s[10:11], 0, v[80:81]
	v_lshl_add_u64 v[44:45], v[44:45], 0, s[96:97]
	v_lshl_add_u64 v[44:45], v[44:45], 0, v[128:129]
	global_store_dwordx2 v[44:45], v[70:71], off
	v_mov_b32_e32 v62, v204
	v_mov_b32_e32 v63, v205
	s_nop 0
	v_mov_b32_e32 v70, v224
	v_mov_b32_e32 v71, v225
	v_mov_b32_e32 v72, v226
	v_mov_b32_e32 v73, v227
	v_mov_b32_e32 v76, v5
	v_mov_b32_e32 v77, v1
	v_mov_b32_e32 v79, v2
	v_mov_b32_e32 v80, v7
	v_mov_b32_e32 v81, v3
	v_lshlrev_b32_e32 v41, 16, v62
	v_mul_f32_e32 v41, 0xbfb8aa3b, v41
	v_exp_f32_e32 v41, v41
	v_and_b32_e32 v65, 0xffff0000, v62
	v_lshlrev_b32_e32 v74, 16, v63
	v_and_b32_e32 v63, 0xffff0000, v63
	v_add_f32_e32 v41, 1.0, v41
	v_rcp_f32_e32 v62, v41
	v_mul_f32_e32 v41, 0xbfb8aa3b, v65
	v_mul_f32_e32 v65, 0xbfb8aa3b, v74
	v_mul_f32_e32 v63, 0xbfb8aa3b, v63
	v_exp_f32_e32 v41, v41
	v_exp_f32_e32 v65, v65
	v_exp_f32_e32 v63, v63
	v_add_f32_e32 v41, 1.0, v41
	v_add_f32_e32 v65, 1.0, v65
	v_add_f32_e32 v63, 1.0, v63
	v_rcp_f32_e32 v74, v65
	v_rcp_f32_e32 v75, v63
	v_rcp_f32_e32 v63, v41
	v_pk_mul_f32 v[58:59], v[58:59], v[74:75]
	v_pk_mul_f32 v[60:61], v[60:61], v[62:63]
	v_pk_mul_f32 v[58:59], v[58:59], v[40:41] op_sel_hi:[1,0]
	v_pk_mul_f32 v[60:61], v[60:61], v[40:41] op_sel_hi:[1,0]
	v_pk_mul_f32 v[58:59], v[72:73], v[58:59]
	v_pk_mul_f32 v[60:61], v[70:71], v[60:61]
	v_mov_b32_e32 v73, v11
	v_cvt_pk_bf16_f32 v60, v60, v61
	v_cvt_pk_bf16_f32 v61, v58, v59
	global_store_dwordx2 v[44:45], v[60:61], off offset:32
	v_mov_b32_e32 v62, v206
	v_mov_b32_e32 v63, v207
	s_nop 0
	v_mov_b32_e32 v58, v228
	v_mov_b32_e32 v59, v229
	v_mov_b32_e32 v60, v230
	v_mov_b32_e32 v61, v231
	v_mov_b32_e32 v74, v4
	v_mov_b32_e32 v75, v0
	v_lshlrev_b32_e32 v41, 16, v62
	v_and_b32_e32 v62, 0xffff0000, v62
	v_lshlrev_b32_e32 v65, 16, v63
	v_and_b32_e32 v63, 0xffff0000, v63
	v_mul_f32_e32 v41, 0xbfb8aa3b, v41
	v_mul_f32_e32 v62, 0xbfb8aa3b, v62
	v_mul_f32_e32 v65, 0xbfb8aa3b, v65
	v_mul_f32_e32 v63, 0xbfb8aa3b, v63
	v_exp_f32_e32 v41, v41
	v_exp_f32_e32 v62, v62
	v_exp_f32_e32 v65, v65
	v_exp_f32_e32 v63, v63
	v_add_f32_e32 v41, 1.0, v41
	v_add_f32_e32 v72, 1.0, v62
	v_add_f32_e32 v65, 1.0, v65
	v_add_f32_e32 v63, 1.0, v63
	v_rcp_f32_e32 v62, v41
	v_rcp_f32_e32 v70, v65
	v_rcp_f32_e32 v71, v63
	v_rcp_f32_e32 v63, v72
	v_mov_b32_e32 v72, v15
	v_pk_mul_f32 v[54:55], v[54:55], v[70:71]
	v_pk_mul_f32 v[62:63], v[82:83], v[62:63]
	v_pk_mul_f32 v[54:55], v[54:55], v[40:41] op_sel_hi:[1,0]
	v_pk_mul_f32 v[62:63], v[62:63], v[40:41] op_sel_hi:[1,0]
	v_pk_mul_f32 v[54:55], v[60:61], v[54:55]
	v_pk_mul_f32 v[58:59], v[58:59], v[62:63]
	v_mov_b32_e32 v70, v14
	v_cvt_pk_bf16_f32 v58, v58, v59
	v_cvt_pk_bf16_f32 v59, v54, v55
	global_store_dwordx2 v[44:45], v[58:59], off offset:64
	v_mov_b32_e32 v54, v208
	v_mov_b32_e32 v55, v209
	s_nop 0
	v_mov_b32_e32 v58, v232
	v_mov_b32_e32 v59, v233
	v_mov_b32_e32 v60, v234
	v_mov_b32_e32 v61, v235
	v_mov_b32_e32 v71, v10
	v_lshlrev_b32_e32 v41, 16, v54
	v_and_b32_e32 v54, 0xffff0000, v54
	v_lshlrev_b32_e32 v62, 16, v55
	v_and_b32_e32 v55, 0xffff0000, v55
	v_mul_f32_e32 v41, 0xbfb8aa3b, v41
	v_mul_f32_e32 v54, 0xbfb8aa3b, v54
	v_mul_f32_e32 v62, 0xbfb8aa3b, v62
	v_mul_f32_e32 v55, 0xbfb8aa3b, v55
	v_exp_f32_e32 v41, v41
	v_exp_f32_e32 v54, v54
	v_exp_f32_e32 v62, v62
	v_exp_f32_e32 v55, v55
	v_add_f32_e32 v41, 1.0, v41
	v_add_f32_e32 v65, 1.0, v54
	v_add_f32_e32 v62, 1.0, v62
	v_add_f32_e32 v55, 1.0, v55
	v_rcp_f32_e32 v54, v41
	v_rcp_f32_e32 v62, v62
	v_rcp_f32_e32 v63, v55
	v_rcp_f32_e32 v55, v65
	v_pk_mul_f32 v[50:51], v[50:51], v[62:63]
	v_pk_mul_f32 v[54:55], v[66:67], v[54:55]
	v_pk_mul_f32 v[50:51], v[50:51], v[40:41] op_sel_hi:[1,0]
	v_pk_mul_f32 v[54:55], v[54:55], v[40:41] op_sel_hi:[1,0]
	v_pk_mul_f32 v[50:51], v[60:61], v[50:51]
	v_pk_mul_f32 v[54:55], v[58:59], v[54:55]
	v_mov_b32_e32 v63, v8
	v_cvt_pk_bf16_f32 v54, v54, v55
	v_cvt_pk_bf16_f32 v55, v50, v51
	global_store_dwordx2 v[44:45], v[54:55], off offset:96
	v_mov_b32_e32 v50, v210
	v_mov_b32_e32 v51, v211
	v_mov_b32_e32 v58, v236
	v_mov_b32_e32 v59, v237
	v_mov_b32_e32 v60, v238
	v_mov_b32_e32 v61, v239
	v_mov_b32_e32 v66, v13
	v_mov_b32_e32 v67, v9
	v_lshlrev_b32_e32 v41, 16, v50
	v_and_b32_e32 v50, 0xffff0000, v50
	v_lshlrev_b32_e32 v54, 16, v51
	v_and_b32_e32 v51, 0xffff0000, v51
	v_mul_f32_e32 v41, 0xbfb8aa3b, v41
	v_mul_f32_e32 v50, 0xbfb8aa3b, v50
	v_mul_f32_e32 v54, 0xbfb8aa3b, v54
	v_mul_f32_e32 v51, 0xbfb8aa3b, v51
	v_exp_f32_e32 v41, v41
	v_exp_f32_e32 v50, v50
	v_exp_f32_e32 v54, v54
	v_exp_f32_e32 v51, v51
	v_add_f32_e32 v41, 1.0, v41
	v_add_f32_e32 v62, 1.0, v50
	v_add_f32_e32 v54, 1.0, v54
	v_add_f32_e32 v51, 1.0, v51
	v_rcp_f32_e32 v50, v41
	v_rcp_f32_e32 v54, v54
	v_rcp_f32_e32 v55, v51
	v_rcp_f32_e32 v51, v62
	v_mov_b32_e32 v62, v12
	v_pk_mul_f32 v[46:47], v[46:47], v[54:55]
	v_pk_mul_f32 v[50:51], v[56:57], v[50:51]
	v_pk_mul_f32 v[46:47], v[46:47], v[40:41] op_sel_hi:[1,0]
	v_pk_mul_f32 v[50:51], v[50:51], v[40:41] op_sel_hi:[1,0]
	v_pk_mul_f32 v[46:47], v[60:61], v[46:47]
	v_pk_mul_f32 v[50:51], v[58:59], v[50:51]
	v_mov_b32_e32 v59, v18
	v_cvt_pk_bf16_f32 v50, v50, v51
	v_cvt_pk_bf16_f32 v51, v46, v47
	global_store_dwordx2 v[44:45], v[50:51], off offset:128
	v_mov_b32_e32 v46, v216
	v_mov_b32_e32 v47, v217
	global_load_dwordx4 v[54:57], v68, s[30:31] offset:320
	v_mov_b32_e32 v60, v23
	v_mov_b32_e32 v61, v19
	v_lshlrev_b32_e32 v41, 16, v46
	v_and_b32_e32 v46, 0xffff0000, v46
	v_lshlrev_b32_e32 v50, 16, v47
	v_and_b32_e32 v47, 0xffff0000, v47
	v_mul_f32_e32 v41, 0xbfb8aa3b, v41
	v_mul_f32_e32 v46, 0xbfb8aa3b, v46
	v_mul_f32_e32 v50, 0xbfb8aa3b, v50
	v_mul_f32_e32 v47, 0xbfb8aa3b, v47
	v_exp_f32_e32 v41, v41
	v_exp_f32_e32 v46, v46
	v_exp_f32_e32 v50, v50
	v_exp_f32_e32 v47, v47
	v_add_f32_e32 v41, 1.0, v41
	v_add_f32_e32 v58, 1.0, v46
	v_add_f32_e32 v50, 1.0, v50
	v_add_f32_e32 v47, 1.0, v47
	v_rcp_f32_e32 v46, v41
	v_rcp_f32_e32 v50, v50
	v_rcp_f32_e32 v51, v47
	v_rcp_f32_e32 v47, v58
	v_mov_b32_e32 v58, v22
	v_pk_mul_f32 v[42:43], v[42:43], v[50:51]
	v_pk_mul_f32 v[46:47], v[52:53], v[46:47]
	v_pk_mul_f32 v[42:43], v[40:41], v[42:43] op_sel_hi:[0,1]
	v_pk_mul_f32 v[46:47], v[40:41], v[46:47] op_sel_hi:[0,1]
	s_waitcnt vmcnt(0)
	v_pk_mul_f32 v[42:43], v[56:57], v[42:43]
	v_pk_mul_f32 v[46:47], v[54:55], v[46:47]
	v_mov_b32_e32 v55, v16
	v_cvt_pk_bf16_f32 v46, v46, v47
	v_cvt_pk_bf16_f32 v47, v42, v43
	global_store_dwordx2 v[44:45], v[46:47], off offset:160
	v_mov_b32_e32 v42, v218
	v_mov_b32_e32 v43, v219
	global_load_dwordx4 v[50:53], v68, s[30:31] offset:384
	v_mov_b32_e32 v56, v21
	v_mov_b32_e32 v57, v17
	v_lshlrev_b32_e32 v41, 16, v42
	v_and_b32_e32 v42, 0xffff0000, v42
	v_lshlrev_b32_e32 v46, 16, v43
	v_and_b32_e32 v43, 0xffff0000, v43
	v_mul_f32_e32 v41, 0xbfb8aa3b, v41
	v_mul_f32_e32 v42, 0xbfb8aa3b, v42
	v_mul_f32_e32 v46, 0xbfb8aa3b, v46
	v_mul_f32_e32 v43, 0xbfb8aa3b, v43
	v_exp_f32_e32 v41, v41
	v_exp_f32_e32 v42, v42
	v_exp_f32_e32 v46, v46
	v_exp_f32_e32 v43, v43
	v_add_f32_e32 v41, 1.0, v41
	v_add_f32_e32 v54, 1.0, v42
	v_add_f32_e32 v46, 1.0, v46
	v_add_f32_e32 v43, 1.0, v43
	v_rcp_f32_e32 v42, v41
	v_rcp_f32_e32 v46, v46
	v_rcp_f32_e32 v47, v43
	v_rcp_f32_e32 v43, v54
	v_mov_b32_e32 v54, v20
	v_pk_mul_f32 v[38:39], v[38:39], v[46:47]
	v_pk_mul_f32 v[36:37], v[36:37], v[42:43]
	v_pk_mul_f32 v[38:39], v[40:41], v[38:39] op_sel_hi:[0,1]
	v_pk_mul_f32 v[36:37], v[40:41], v[36:37] op_sel_hi:[0,1]
	s_waitcnt vmcnt(0)
	v_pk_mul_f32 v[38:39], v[52:53], v[38:39]
	v_pk_mul_f32 v[36:37], v[50:51], v[36:37]
	v_mov_b32_e32 v42, v29
	v_cvt_pk_bf16_f32 v36, v36, v37
	v_cvt_pk_bf16_f32 v37, v38, v39
	global_store_dwordx2 v[44:45], v[36:37], off offset:192
	v_mov_b32_e32 v36, v220
	v_mov_b32_e32 v37, v221
	v_mov_b32_e32 v38, v28
	global_load_dwordx4 v[46:49], v68, s[30:31] offset:448
	v_mov_b32_e32 v39, v24
	v_mov_b32_e32 v43, v25
	v_mov_b32_e32 v50, v30
	v_mov_b32_e32 v51, v26
	v_pk_add_f32 v[38:39], v[38:39], v[42:43]
	v_mov_b32_e32 v52, v31
	v_mov_b32_e32 v53, v27
	v_pk_add_f32 v[38:39], v[50:51], v[38:39]
	v_pk_add_f32 v[42:43], v[54:55], v[56:57]
	v_pk_add_f32 v[38:39], v[52:53], v[38:39]
	v_pk_add_f32 v[42:43], v[58:59], v[42:43]
	v_add_f32_e32 v38, 0, v38
	v_pk_add_f32 v[54:55], v[62:63], v[66:67]
	v_pk_add_f32 v[42:43], v[60:61], v[42:43]
	v_add_f32_e32 v38, v38, v39
	v_pk_add_f32 v[50:51], v[70:71], v[54:55]
	v_add_f32_e32 v38, v38, v42
	v_pk_add_f32 v[56:57], v[74:75], v[76:77]
	v_pk_add_f32 v[50:51], v[72:73], v[50:51]
	v_add_f32_e32 v38, v38, v43
	v_pk_add_f32 v[54:55], v[78:79], v[56:57]
	v_add_f32_e32 v38, v38, v50
	v_pk_add_f32 v[52:53], v[80:81], v[54:55]
	v_add_f32_e32 v38, v38, v51
	v_add_f32_e32 v38, v38, v52
	v_add_f32_e32 v41, v38, v53
	v_add_u32_e32 v62, 16, v64
	ds_bpermute_b32 v50, v109, v41
	v_ashrrev_i32_e32 v63, 31, v62
	v_lshlrev_b64 v[38:39], 14, v[62:63]
	v_lshl_add_u64 v[38:39], s[52:53], 0, v[38:39]
	v_lshl_add_u64 v[38:39], v[38:39], 0, s[96:97]
	v_lshl_add_u64 v[42:43], v[38:39], 0, v[128:129]
	s_waitcnt lgkmcnt(0)
	v_add_f32_e32 v38, v41, v50
	ds_bpermute_b32 v39, v154, v38
	v_add_co_u32_e32 v50, vcc, s38, v42
	s_waitcnt lgkmcnt(0)
	v_add_f32_e32 v38, v38, v39
	v_fmamk_f32 v54, v38, 0xbc000000, v28
	v_fmamk_f32 v55, v38, 0xbc000000, v29
	v_addc_co_u32_e32 v51, vcc, 0, v43, vcc
	v_mul_f32_e32 v39, v55, v55
	v_fmamk_f32 v30, v38, 0xbc000000, v30
	v_fmac_f32_e32 v39, v54, v54
	v_fmac_f32_e32 v31, 0xbc000000, v38
	v_fmac_f32_e32 v39, v30, v30
	v_fmac_f32_e32 v39, v31, v31
	v_fmamk_f32 v26, v38, 0xbc000000, v26
	v_fmac_f32_e32 v27, 0xbc000000, v38
	v_fmamk_f32 v22, v38, 0xbc000000, v22
	v_fmac_f32_e32 v23, 0xbc000000, v38
	v_fmamk_f32 v18, v38, 0xbc000000, v18
	v_fmac_f32_e32 v19, 0xbc000000, v38
	v_fmamk_f32 v14, v38, 0xbc000000, v14
	v_fmac_f32_e32 v15, 0xbc000000, v38
	v_mul_f32_e32 v52, 0x3c000000, v38
	v_fmamk_f32 v10, v38, 0xbc000000, v10
	v_fmac_f32_e32 v11, 0xbc000000, v38
	v_lshlrev_b32_e32 v28, 16, v36
	v_and_b32_e32 v29, 0xffff0000, v36
	v_lshlrev_b32_e32 v36, 16, v37
	v_and_b32_e32 v37, 0xffff0000, v37
	v_mul_f32_e32 v28, 0xbfb8aa3b, v28
	v_mul_f32_e32 v29, 0xbfb8aa3b, v29
	v_mul_f32_e32 v36, 0xbfb8aa3b, v36
	v_mul_f32_e32 v37, 0xbfb8aa3b, v37
	v_exp_f32_e32 v28, v28
	v_exp_f32_e32 v29, v29
	v_exp_f32_e32 v36, v36
	v_exp_f32_e32 v37, v37
	v_add_f32_e32 v28, 1.0, v28
	v_add_f32_e32 v29, 1.0, v29
	v_add_f32_e32 v36, 1.0, v36
	v_add_f32_e32 v37, 1.0, v37
	v_rcp_f32_e32 v28, v28
	v_rcp_f32_e32 v36, v36
	v_rcp_f32_e32 v37, v37
	v_rcp_f32_e32 v29, v29
	v_pk_mul_f32 v[34:35], v[34:35], v[36:37]
	v_pk_mul_f32 v[28:29], v[32:33], v[28:29]
	v_pk_mul_f32 v[32:33], v[40:41], v[34:35] op_sel_hi:[0,1]
	v_pk_mul_f32 v[28:29], v[40:41], v[28:29] op_sel_hi:[0,1]
	s_waitcnt vmcnt(0)
	v_pk_mul_f32 v[32:33], v[48:49], v[32:33]
	v_pk_mul_f32 v[28:29], v[46:47], v[28:29]
	v_pk_add_f32 v[46:47], v[2:3], v[52:53] op_sel_hi:[1,0] neg_lo:[0,1] neg_hi:[0,1]
	v_cvt_pk_bf16_f32 v28, v28, v29
	v_cvt_pk_bf16_f32 v29, v32, v33
	global_store_dwordx2 v[44:45], v[28:29], off offset:224
	global_load_dwordx2 v[40:41], v[50:51], off offset:2048
	global_load_dwordx4 v[34:37], v68, s[30:31]
	v_fmamk_f32 v44, v38, 0xbc000000, v24
	v_fmamk_f32 v45, v38, 0xbc000000, v25
	v_fmac_f32_e32 v39, v44, v44
	v_fmac_f32_e32 v39, v45, v45
	v_fmac_f32_e32 v39, v26, v26
	v_fmamk_f32 v32, v38, 0xbc000000, v20
	v_fmac_f32_e32 v39, v27, v27
	v_fmamk_f32 v33, v38, 0xbc000000, v21
	v_fmac_f32_e32 v39, v32, v32
	v_fmac_f32_e32 v39, v33, v33
	v_fmac_f32_e32 v39, v22, v22
	v_fmamk_f32 v28, v38, 0xbc000000, v16
	v_fmac_f32_e32 v39, v23, v23
	v_fmamk_f32 v29, v38, 0xbc000000, v17
	v_fmac_f32_e32 v39, v28, v28
	v_fmac_f32_e32 v39, v29, v29
	v_fmac_f32_e32 v39, v18, v18
	v_fmamk_f32 v24, v38, 0xbc000000, v12
	v_fmac_f32_e32 v39, v19, v19
	v_fmamk_f32 v25, v38, 0xbc000000, v13
	v_fmac_f32_e32 v39, v24, v24
	v_fmac_f32_e32 v39, v25, v25
	v_fmac_f32_e32 v39, v14, v14
	v_fmamk_f32 v16, v38, 0xbc000000, v8
	v_fmac_f32_e32 v39, v15, v15
	v_fmamk_f32 v17, v38, 0xbc000000, v9
	v_fmac_f32_e32 v39, v16, v16
	v_fmac_f32_e32 v39, v17, v17
	v_pk_add_f32 v[8:9], v[4:5], v[52:53] op_sel_hi:[1,0] neg_lo:[0,1] neg_hi:[0,1]
	v_fmac_f32_e32 v39, v10, v10
	v_pk_mul_f32 v[8:9], v[8:9], v[8:9]
	v_fmac_f32_e32 v39, v11, v11
	v_pk_add_f32 v[12:13], v[6:7], v[52:53] op_sel_hi:[1,0] neg_lo:[0,1] neg_hi:[0,1]
	v_add_f32_e32 v8, v8, v39
	v_pk_mul_f32 v[12:13], v[12:13], v[12:13]
	v_add_f32_e32 v8, v9, v8
	v_pk_add_f32 v[20:21], v[0:1], v[52:53] op_sel_hi:[1,0] neg_lo:[0,1] neg_hi:[0,1]
	v_add_f32_e32 v8, v12, v8
	v_pk_mul_f32 v[20:21], v[20:21], v[20:21]
	v_add_f32_e32 v8, v13, v8
	v_add_f32_e32 v8, v20, v8
	v_pk_mul_f32 v[46:47], v[46:47], v[46:47]
	v_add_f32_e32 v8, v21, v8
	v_add_f32_e32 v8, v46, v8
	v_add_f32_e32 v12, v47, v8
	ds_bpermute_b32 v13, v109, v12
	v_lshl_add_u64 v[20:21], v[42:43], 0, s[40:41]
	global_load_dwordx2 v[222:223], v[20:21], off offset:32
	global_load_dwordx2 v[224:225], v[20:21], off offset:64
	global_load_dwordx2 v[226:227], v[20:21], off offset:96
	global_load_dwordx2 v[228:229], v[20:21], off offset:128
	global_load_dwordx2 v[230:231], v[20:21], off offset:160
	global_load_dwordx2 v[232:233], v[20:21], off offset:192
	global_load_dwordx2 v[234:235], v[20:21], off offset:224
	global_load_dwordx4 v[204:207], v68, s[30:31] offset:64
	global_load_dwordx4 v[208:211], v68, s[30:31] offset:128
	global_load_dwordx4 v[216:219], v68, s[30:31] offset:192
	global_load_dwordx4 v[236:239], v68, s[30:31] offset:256
	v_lshlrev_b64 v[8:9], 11, v[62:63]
	v_lshl_add_u64 v[8:9], s[10:11], 0, v[8:9]
	v_lshl_add_u64 v[8:9], v[8:9], 0, s[96:97]
	s_waitcnt lgkmcnt(0)
	v_add_f32_e32 v12, v12, v13
	ds_bpermute_b32 v13, v154, v12
	v_lshl_add_u64 v[8:9], v[8:9], 0, v[128:129]
	v_fmamk_f32 v5, v38, 0xbc000000, v5
	v_fmamk_f32 v4, v38, 0xbc000000, v4
	v_fmamk_f32 v7, v38, 0xbc000000, v7
	s_waitcnt lgkmcnt(0)
	v_add_f32_e32 v12, v12, v13
	v_fmamk_f32 v12, v12, 0x3c000000, v163
	v_mul_f32_e32 v13, 0x4b800000, v12
	v_cmp_gt_f32_e32 vcc, s2, v12
	v_fmac_f32_e32 v6, 0xbc000000, v38
	v_fmamk_f32 v1, v38, 0xbc000000, v1
	v_cndmask_b32_e32 v12, v12, v13, vcc
	v_rsq_f32_e32 v12, v12
	v_fmamk_f32 v0, v38, 0xbc000000, v0
	v_fmamk_f32 v3, v38, 0xbc000000, v3
	v_fmac_f32_e32 v2, 0xbc000000, v38
	s_waitcnt vmcnt(1)
	v_lshlrev_b32_e32 v13, 16, v40
	v_and_b32_e32 v39, 0xffff0000, v40
	v_lshlrev_b32_e32 v40, 16, v41
	v_and_b32_e32 v41, 0xffff0000, v41
	v_mul_f32_e32 v13, 0xbfb8aa3b, v13
	v_mul_f32_e32 v39, 0xbfb8aa3b, v39
	v_mul_f32_e32 v40, 0xbfb8aa3b, v40
	v_mul_f32_e32 v41, 0xbfb8aa3b, v41
	v_exp_f32_e32 v13, v13
	v_exp_f32_e32 v39, v39
	v_exp_f32_e32 v40, v40
	v_exp_f32_e32 v41, v41
	v_add_f32_e32 v13, 1.0, v13
	v_add_f32_e32 v39, 1.0, v39
	v_add_f32_e32 v42, 1.0, v40
	v_add_f32_e32 v41, 1.0, v41
	v_rcp_f32_e32 v40, v13
	v_rcp_f32_e32 v42, v42
	v_rcp_f32_e32 v43, v41
	v_rcp_f32_e32 v41, v39
	v_mul_f32_e32 v13, 0x45800000, v12
	v_cndmask_b32_e32 v12, v12, v13, vcc
	v_pk_mul_f32 v[30:31], v[30:31], v[42:43]
	v_pk_mul_f32 v[40:41], v[54:55], v[40:41]
	v_pk_mul_f32 v[30:31], v[30:31], v[12:13] op_sel_hi:[1,0]
	v_pk_mul_f32 v[40:41], v[40:41], v[12:13] op_sel_hi:[1,0]
	s_waitcnt vmcnt(0)
	v_pk_mul_f32 v[30:31], v[36:37], v[30:31]
	v_pk_mul_f32 v[34:35], v[34:35], v[40:41]
	s_nop 0
	v_cvt_pk_bf16_f32 v34, v34, v35
	v_cvt_pk_bf16_f32 v35, v30, v31
	global_store_dwordx2 v[8:9], v[34:35], off
	v_mov_b32_e32 v30, v222
	v_mov_b32_e32 v31, v223
	s_nop 0
	v_mov_b32_e32 v34, v204
	v_mov_b32_e32 v35, v205
	v_mov_b32_e32 v36, v206
	v_mov_b32_e32 v37, v207
	v_lshlrev_b32_e32 v13, 16, v30
	v_and_b32_e32 v30, 0xffff0000, v30
	v_lshlrev_b32_e32 v39, 16, v31
	v_and_b32_e32 v31, 0xffff0000, v31
	v_mul_f32_e32 v13, 0xbfb8aa3b, v13
	v_mul_f32_e32 v30, 0xbfb8aa3b, v30
	v_mul_f32_e32 v39, 0xbfb8aa3b, v39
	v_mul_f32_e32 v31, 0xbfb8aa3b, v31
	v_exp_f32_e32 v13, v13
	v_exp_f32_e32 v30, v30
	v_exp_f32_e32 v39, v39
	v_exp_f32_e32 v31, v31
	v_add_f32_e32 v13, 1.0, v13
	v_add_f32_e32 v42, 1.0, v30
	v_add_f32_e32 v39, 1.0, v39
	v_add_f32_e32 v31, 1.0, v31
	v_rcp_f32_e32 v30, v13
	v_rcp_f32_e32 v40, v39
	v_rcp_f32_e32 v41, v31
	v_rcp_f32_e32 v31, v42
	v_pk_mul_f32 v[26:27], v[26:27], v[40:41]
	v_pk_mul_f32 v[30:31], v[44:45], v[30:31]
	v_pk_mul_f32 v[26:27], v[26:27], v[12:13] op_sel_hi:[1,0]
	v_pk_mul_f32 v[30:31], v[30:31], v[12:13] op_sel_hi:[1,0]
	v_pk_mul_f32 v[26:27], v[36:37], v[26:27]
	v_pk_mul_f32 v[30:31], v[34:35], v[30:31]
	s_nop 0
	v_cvt_pk_bf16_f32 v30, v30, v31
	v_cvt_pk_bf16_f32 v31, v26, v27
	global_store_dwordx2 v[8:9], v[30:31], off offset:32
	v_mov_b32_e32 v26, v224
	v_mov_b32_e32 v27, v225
	v_mov_b32_e32 v34, v208
	v_mov_b32_e32 v35, v209
	v_mov_b32_e32 v36, v210
	v_mov_b32_e32 v37, v211
	v_lshlrev_b32_e32 v13, 16, v26
	v_and_b32_e32 v26, 0xffff0000, v26
	v_lshlrev_b32_e32 v30, 16, v27
	v_and_b32_e32 v27, 0xffff0000, v27
	v_mul_f32_e32 v13, 0xbfb8aa3b, v13
	v_mul_f32_e32 v26, 0xbfb8aa3b, v26
	v_mul_f32_e32 v30, 0xbfb8aa3b, v30
	v_mul_f32_e32 v27, 0xbfb8aa3b, v27
	v_exp_f32_e32 v13, v13
	v_exp_f32_e32 v26, v26
	v_exp_f32_e32 v30, v30
	v_exp_f32_e32 v27, v27
	v_add_f32_e32 v13, 1.0, v13
	v_add_f32_e32 v39, 1.0, v26
	v_add_f32_e32 v30, 1.0, v30
	v_add_f32_e32 v27, 1.0, v27
	v_rcp_f32_e32 v26, v13
	v_rcp_f32_e32 v30, v30
	v_rcp_f32_e32 v31, v27
	v_rcp_f32_e32 v27, v39
	v_pk_mul_f32 v[22:23], v[22:23], v[30:31]
	v_pk_mul_f32 v[26:27], v[32:33], v[26:27]
	v_pk_mul_f32 v[22:23], v[22:23], v[12:13] op_sel_hi:[1,0]
	v_pk_mul_f32 v[26:27], v[26:27], v[12:13] op_sel_hi:[1,0]
	v_pk_mul_f32 v[22:23], v[36:37], v[22:23]
	v_pk_mul_f32 v[26:27], v[34:35], v[26:27]
	s_nop 0
	v_cvt_pk_bf16_f32 v26, v26, v27
	v_cvt_pk_bf16_f32 v27, v22, v23
	global_store_dwordx2 v[8:9], v[26:27], off offset:64
	v_mov_b32_e32 v22, v226
	v_mov_b32_e32 v23, v227
	v_mov_b32_e32 v30, v216
	v_mov_b32_e32 v31, v217
	v_mov_b32_e32 v32, v218
	v_mov_b32_e32 v33, v219
	v_lshlrev_b32_e32 v13, 16, v22
	v_and_b32_e32 v22, 0xffff0000, v22
	v_lshlrev_b32_e32 v26, 16, v23
	v_and_b32_e32 v23, 0xffff0000, v23
	v_mul_f32_e32 v13, 0xbfb8aa3b, v13
	v_mul_f32_e32 v22, 0xbfb8aa3b, v22
	v_mul_f32_e32 v26, 0xbfb8aa3b, v26
	v_mul_f32_e32 v23, 0xbfb8aa3b, v23
	v_exp_f32_e32 v13, v13
	v_exp_f32_e32 v22, v22
	v_exp_f32_e32 v26, v26
	v_exp_f32_e32 v23, v23
	v_add_f32_e32 v13, 1.0, v13
	v_add_f32_e32 v34, 1.0, v22
	v_add_f32_e32 v26, 1.0, v26
	v_add_f32_e32 v23, 1.0, v23
	v_rcp_f32_e32 v22, v13
	v_rcp_f32_e32 v26, v26
	v_rcp_f32_e32 v27, v23
	v_rcp_f32_e32 v23, v34
	v_pk_mul_f32 v[18:19], v[18:19], v[26:27]
	v_pk_mul_f32 v[22:23], v[28:29], v[22:23]
	v_pk_mul_f32 v[18:19], v[18:19], v[12:13] op_sel_hi:[1,0]
	v_pk_mul_f32 v[22:23], v[22:23], v[12:13] op_sel_hi:[1,0]
	v_pk_mul_f32 v[18:19], v[32:33], v[18:19]
	v_pk_mul_f32 v[22:23], v[30:31], v[22:23]
	s_nop 0
	v_cvt_pk_bf16_f32 v22, v22, v23
	v_cvt_pk_bf16_f32 v23, v18, v19
	global_store_dwordx2 v[8:9], v[22:23], off offset:96
	v_mov_b32_e32 v18, v228
	v_mov_b32_e32 v19, v229
	v_mov_b32_e32 v26, v236
	v_mov_b32_e32 v27, v237
	v_mov_b32_e32 v28, v238
	v_mov_b32_e32 v29, v239
	v_lshlrev_b32_e32 v13, 16, v18
	v_and_b32_e32 v18, 0xffff0000, v18
	v_lshlrev_b32_e32 v22, 16, v19
	v_and_b32_e32 v19, 0xffff0000, v19
	v_mul_f32_e32 v13, 0xbfb8aa3b, v13
	v_mul_f32_e32 v18, 0xbfb8aa3b, v18
	v_mul_f32_e32 v22, 0xbfb8aa3b, v22
	v_mul_f32_e32 v19, 0xbfb8aa3b, v19
	v_exp_f32_e32 v13, v13
	v_exp_f32_e32 v18, v18
	v_exp_f32_e32 v22, v22
	v_exp_f32_e32 v19, v19
	v_add_f32_e32 v13, 1.0, v13
	v_add_f32_e32 v30, 1.0, v18
	v_add_f32_e32 v22, 1.0, v22
	v_add_f32_e32 v19, 1.0, v19
	v_rcp_f32_e32 v18, v13
	v_rcp_f32_e32 v22, v22
	v_rcp_f32_e32 v23, v19
	v_rcp_f32_e32 v19, v30
	v_pk_mul_f32 v[14:15], v[14:15], v[22:23]
	v_pk_mul_f32 v[18:19], v[24:25], v[18:19]
	v_pk_mul_f32 v[14:15], v[14:15], v[12:13] op_sel_hi:[1,0]
	v_pk_mul_f32 v[18:19], v[18:19], v[12:13] op_sel_hi:[1,0]
	v_pk_mul_f32 v[14:15], v[28:29], v[14:15]
	v_pk_mul_f32 v[18:19], v[26:27], v[18:19]
	s_nop 0
	v_cvt_pk_bf16_f32 v18, v18, v19
	v_cvt_pk_bf16_f32 v19, v14, v15
	global_store_dwordx2 v[8:9], v[18:19], off offset:128
	v_mov_b32_e32 v14, v230
	v_mov_b32_e32 v15, v231
	global_load_dwordx4 v[22:25], v68, s[30:31] offset:320
	v_lshlrev_b32_e32 v13, 16, v14
	v_and_b32_e32 v14, 0xffff0000, v14
	v_lshlrev_b32_e32 v18, 16, v15
	v_and_b32_e32 v15, 0xffff0000, v15
	v_mul_f32_e32 v13, 0xbfb8aa3b, v13
	v_mul_f32_e32 v14, 0xbfb8aa3b, v14
	v_mul_f32_e32 v18, 0xbfb8aa3b, v18
	v_mul_f32_e32 v15, 0xbfb8aa3b, v15
	v_exp_f32_e32 v13, v13
	v_exp_f32_e32 v14, v14
	v_exp_f32_e32 v18, v18
	v_exp_f32_e32 v15, v15
	v_add_f32_e32 v13, 1.0, v13
	v_add_f32_e32 v26, 1.0, v14
	v_add_f32_e32 v18, 1.0, v18
	v_add_f32_e32 v15, 1.0, v15
	v_rcp_f32_e32 v14, v13
	v_rcp_f32_e32 v18, v18
	v_rcp_f32_e32 v19, v15
	v_rcp_f32_e32 v15, v26
	v_pk_mul_f32 v[10:11], v[10:11], v[18:19]
	v_pk_mul_f32 v[14:15], v[16:17], v[14:15]
	v_pk_mul_f32 v[10:11], v[12:13], v[10:11] op_sel_hi:[0,1]
	v_pk_mul_f32 v[14:15], v[12:13], v[14:15] op_sel_hi:[0,1]
	s_waitcnt vmcnt(0)
	v_pk_mul_f32 v[10:11], v[24:25], v[10:11]
	v_pk_mul_f32 v[14:15], v[22:23], v[14:15]
	s_nop 0
	v_cvt_pk_bf16_f32 v14, v14, v15
	v_cvt_pk_bf16_f32 v15, v10, v11
	global_store_dwordx2 v[8:9], v[14:15], off offset:160
	v_mov_b32_e32 v10, v232
	v_mov_b32_e32 v11, v233
	s_nop 0
	global_load_dwordx4 v[14:17], v68, s[30:31] offset:384
	v_lshlrev_b32_e32 v13, 16, v10
	v_and_b32_e32 v10, 0xffff0000, v10
	v_lshlrev_b32_e32 v18, 16, v11
	v_and_b32_e32 v11, 0xffff0000, v11
	v_mul_f32_e32 v13, 0xbfb8aa3b, v13
	v_mul_f32_e32 v10, 0xbfb8aa3b, v10
	v_mul_f32_e32 v18, 0xbfb8aa3b, v18
	v_mul_f32_e32 v11, 0xbfb8aa3b, v11
	v_exp_f32_e32 v13, v13
	v_exp_f32_e32 v10, v10
	v_exp_f32_e32 v18, v18
	v_exp_f32_e32 v11, v11
	v_add_f32_e32 v13, 1.0, v13
	v_add_f32_e32 v22, 1.0, v10
	v_add_f32_e32 v18, 1.0, v18
	v_add_f32_e32 v11, 1.0, v11
	v_rcp_f32_e32 v10, v13
	v_rcp_f32_e32 v18, v18
	v_rcp_f32_e32 v19, v11
	v_rcp_f32_e32 v11, v22
	v_pk_mul_f32 v[6:7], v[6:7], v[18:19]
	v_pk_mul_f32 v[4:5], v[4:5], v[10:11]
	v_pk_mul_f32 v[6:7], v[12:13], v[6:7] op_sel_hi:[0,1]
	v_pk_mul_f32 v[4:5], v[12:13], v[4:5] op_sel_hi:[0,1]
	s_waitcnt vmcnt(0)
	v_pk_mul_f32 v[6:7], v[16:17], v[6:7]
	v_pk_mul_f32 v[4:5], v[14:15], v[4:5]
	s_nop 0
	v_cvt_pk_bf16_f32 v4, v4, v5
	v_cvt_pk_bf16_f32 v5, v6, v7
	global_store_dwordx2 v[8:9], v[4:5], off offset:192
	v_mov_b32_e32 v10, v234
	v_mov_b32_e32 v11, v235
	s_nop 0
	global_load_dwordx4 v[4:7], v68, s[30:31] offset:448
	v_lshlrev_b32_e32 v13, 16, v10
	v_and_b32_e32 v10, 0xffff0000, v10
	v_lshlrev_b32_e32 v14, 16, v11
	v_and_b32_e32 v11, 0xffff0000, v11
	v_mul_f32_e32 v13, 0xbfb8aa3b, v13
	v_mul_f32_e32 v10, 0xbfb8aa3b, v10
	v_mul_f32_e32 v14, 0xbfb8aa3b, v14
	v_mul_f32_e32 v11, 0xbfb8aa3b, v11
	v_exp_f32_e32 v13, v13
	v_exp_f32_e32 v10, v10
	v_exp_f32_e32 v14, v14
	v_exp_f32_e32 v11, v11
	v_add_f32_e32 v13, 1.0, v13
	v_add_f32_e32 v16, 1.0, v10
	v_add_f32_e32 v14, 1.0, v14
	v_add_f32_e32 v11, 1.0, v11
	v_rcp_f32_e32 v10, v13
	v_rcp_f32_e32 v14, v14
	v_rcp_f32_e32 v15, v11
	v_rcp_f32_e32 v11, v16
	v_pk_mul_f32 v[2:3], v[2:3], v[14:15]
	v_pk_mul_f32 v[0:1], v[0:1], v[10:11]
	v_pk_mul_f32 v[2:3], v[12:13], v[2:3] op_sel_hi:[0,1]
	v_pk_mul_f32 v[0:1], v[12:13], v[0:1] op_sel_hi:[0,1]
	s_waitcnt vmcnt(0)
	v_pk_mul_f32 v[2:3], v[6:7], v[2:3]
	v_pk_mul_f32 v[0:1], v[4:5], v[0:1]
	s_nop 0
	v_cvt_pk_bf16_f32 v0, v0, v1
	v_cvt_pk_bf16_f32 v1, v2, v3
	global_store_dwordx2 v[8:9], v[0:1], off offset:224
	s_cbranch_scc1 .LBB1_806
